# P6 balance: prompt tile 0 taken as four one-sub-block trips by workgroups 129..132 (interior states from workgroup 0's P5 scan) instead of a second whole tile on workgroup 128
# speedup vs baseline: 1.0128x; 1.0013x over previous
; template <bool PASS2>
; __device__ __forceinline__ void s5_tile(const Ctx& C, int T, int sb_lo, int sb_hi, LAS unsigned char* lds, int wave, int lane) {
;     ...
;     for (int sb = sb_lo; sb < sb_hi; ++sb) {
;         const int rb0 = r0 + 32 * sb;
; #pragma unroll
;         for (int i = 0; i < 4; ++i) *(LAS v4u*)(XU + (xrow + 8 * i) * XU_STRIDE + 8 * xpart) = xn[i];
;         if (sb + 1 < sb_hi) {
; #pragma unroll
;             for (int i = 0; i < 4; ++i) xn[i] = *(const v4u*)(Zb + (size_t)(rb0 + 32 + xrow + 8 * i) * DIN + 8 * xpart);
;         }
;         LDS_FENCE();
; #pragma unroll
;         for (int gi = 0; gi < 4; ++gi) {
;             const int g = wave * 4 + gi, gnx = wave * 4 + ((gi + 1) & 3);
;             bfx8 bb[4], cm[4];
; #pragma unroll
;             for (int cb = 0; cb < 4; ++cb) { bb[cb] = bbn[cb]; bbn[cb] = *(const bfx8*)(BBt + ((size_t)(gnx * 128 + cb * 32 + tl)) * GN + 8 * hh); }
;             if (PASS2) {
; #pragma unroll
;                 for (int ks = 0; ks < 4; ++ks) { cm[ks] = cmn[ks]; cmn[ks] = *(const bfx8*)(CMt + ((size_t)(gnx * GN + fr)) * 128 + 32 * ks + 8 * kq); }
;             }
;             float s0ar = 0.f, s0ai = 0.f, s0br = 0.f, s0bi = 0.f;
;             if (sample) { const size_t o0 = ((size_t)(2 * sb) * NG + g) * NP + lane, o1 = o0 + (size_t)NG * NP;
;                 s0ar = C.in(2)[o0]; s0ai = C.in(3)[o0]; s0br = C.in(2)[o1]; s0bi = C.in(3)[o1]; }
;             const bfx8 a = *(const LAS bfx8*)(XU + tl * XU_STRIDE + 16 * gi + 8 * hh);
; #pragma unroll
;             for (int cb = 0; cb < 4; ++cb) {
;                 v16f acc;
; #pragma unroll
;                 for (int r = 0; r < 16; ++r) acc[r] = 0.f;
;                 acc = __builtin_amdgcn_mfma_f32_32x32x16_bf16(bb[cb], a, acc, 0, 0, 0);
; #pragma unroll
;                 for (int rg = 0; rg < 4; ++rg) { v2u w; w.x = cvt_pk_c(acc[4 * rg], acc[4 * rg + 1]); w.y = cvt_pk_c(acc[4 * rg + 2], acc[4 * rg + 3]);
;                     *(LAS v2u*)(BH + tl * BH_STRIDE + cb * 32 + 8 * rg + 4 * hh) = w; }
;             }
;             LDS_FENCE();
;             {
;                 unsigned bu[32];
; #pragma unroll
;                 for (int t = 0; t < 32; ++t) bu[t] = *(const LAS unsigned*)(BH + t * BH_STRIDE + 2 * lane);
;                 LDS_FENCE();
;                 float xr = sr[gi], xi = si[gi];
; #pragma unroll
;                 for (int t = 0; t < 32; ++t) {
.LBB0_596:
	s_waitcnt lgkmcnt(0)
	ds_read_b128 v[224:227], v101
	global_load_dwordx4 v[60:63], v[112:113], off
	global_load_dwordx4 v[56:59], v[114:115], off
	global_load_dwordx4 v[52:55], v[116:117], off
	global_load_dwordx4 v[48:51], v[118:119], off
	s_waitcnt vmcnt(7) lgkmcnt(0)
	v_mfma_f32_32x32x16_bf16 v[0:15], v[224:227], v[44:47], 0
	s_waitcnt vmcnt(6)
	v_mfma_f32_32x32x16_bf16 v[136:151], v[224:227], v[40:43], 0
	s_waitcnt vmcnt(5)
	v_mfma_f32_32x32x16_bf16 v[192:207], v[224:227], v[36:39], 0
	s_waitcnt vmcnt(4)
	v_mfma_f32_32x32x16_bf16 v[208:223], v[224:227], v[32:35], 0
	s_nop 11
	v_permlane32_swap_b32_e32 v0, v192
	v_permlane32_swap_b32_e32 v1, v193
	v_permlane32_swap_b32_e32 v2, v194
	v_permlane32_swap_b32_e32 v3, v195
	v_permlane32_swap_b32_e32 v4, v196
	v_permlane32_swap_b32_e32 v5, v197
	v_permlane32_swap_b32_e32 v6, v198
	v_permlane32_swap_b32_e32 v7, v199
	v_permlane32_swap_b32_e32 v8, v200
	v_permlane32_swap_b32_e32 v9, v201
	v_permlane32_swap_b32_e32 v10, v202
	v_permlane32_swap_b32_e32 v11, v203
	v_permlane32_swap_b32_e32 v12, v204
	v_permlane32_swap_b32_e32 v13, v205
	v_permlane32_swap_b32_e32 v14, v206
	v_permlane32_swap_b32_e32 v15, v207
	v_permlane32_swap_b32_e32 v136, v208
	v_permlane32_swap_b32_e32 v137, v209
	v_permlane32_swap_b32_e32 v138, v210
	v_permlane32_swap_b32_e32 v139, v211
	v_permlane32_swap_b32_e32 v140, v212
	v_permlane32_swap_b32_e32 v141, v213
	v_permlane32_swap_b32_e32 v142, v214
	v_permlane32_swap_b32_e32 v143, v215
	v_permlane32_swap_b32_e32 v144, v216
	v_permlane32_swap_b32_e32 v145, v217
	v_permlane32_swap_b32_e32 v146, v218
	v_permlane32_swap_b32_e32 v147, v219
	v_permlane32_swap_b32_e32 v148, v220
	v_permlane32_swap_b32_e32 v149, v221
	v_permlane32_swap_b32_e32 v150, v222
	v_permlane32_swap_b32_e32 v151, v223
	v_fma_f32 v0, -v65, v166, v0
	v_fma_f32 v136, v65, v167, v136
	v_fma_f32 v167, v66, v167, v0
	v_fma_f32 v166, v66, v166, v136
	v_fma_f32 v1, -v65, v166, v1
	v_fma_f32 v137, v65, v167, v137
	v_fma_f32 v167, v66, v167, v1
	v_fma_f32 v166, v66, v166, v137
	v_fma_f32 v2, -v65, v166, v2
	v_fma_f32 v138, v65, v167, v138
	v_fma_f32 v167, v66, v167, v2
	v_fma_f32 v166, v66, v166, v138
	v_fma_f32 v3, -v65, v166, v3
	v_fma_f32 v139, v65, v167, v139
	v_fma_f32 v167, v66, v167, v3
	v_fma_f32 v166, v66, v166, v139
	v_fma_f32 v192, -v65, v166, v192
	v_fma_f32 v208, v65, v167, v208
	v_fma_f32 v167, v66, v167, v192
	v_fma_f32 v166, v66, v166, v208
	v_fma_f32 v193, -v65, v166, v193
	v_fma_f32 v209, v65, v167, v209
	v_fma_f32 v167, v66, v167, v193
	v_fma_f32 v166, v66, v166, v209
	v_fma_f32 v194, -v65, v166, v194
	v_fma_f32 v210, v65, v167, v210
	v_fma_f32 v167, v66, v167, v194
	v_fma_f32 v166, v66, v166, v210
	v_fma_f32 v195, -v65, v166, v195
	v_fma_f32 v211, v65, v167, v211
	v_fma_f32 v167, v66, v167, v195
	v_fma_f32 v166, v66, v166, v211
	v_fma_f32 v4, -v65, v166, v4
	v_fma_f32 v140, v65, v167, v140
	v_fma_f32 v167, v66, v167, v4
	v_fma_f32 v166, v66, v166, v140
	v_fma_f32 v5, -v65, v166, v5
	v_fma_f32 v141, v65, v167, v141
	v_fma_f32 v167, v66, v167, v5
	v_fma_f32 v166, v66, v166, v141
	v_fma_f32 v6, -v65, v166, v6
	v_fma_f32 v142, v65, v167, v142
	v_fma_f32 v167, v66, v167, v6
	v_fma_f32 v166, v66, v166, v142
	v_fma_f32 v7, -v65, v166, v7
	v_fma_f32 v143, v65, v167, v143
	v_fma_f32 v167, v66, v167, v7
	v_fma_f32 v166, v66, v166, v143
	v_fma_f32 v196, -v65, v166, v196
	v_fma_f32 v212, v65, v167, v212
	v_fma_f32 v167, v66, v167, v196
	v_fma_f32 v166, v66, v166, v212
	v_fma_f32 v197, -v65, v166, v197
	v_fma_f32 v213, v65, v167, v213
	v_fma_f32 v167, v66, v167, v197
	v_fma_f32 v166, v66, v166, v213
	v_fma_f32 v198, -v65, v166, v198
	v_fma_f32 v214, v65, v167, v214
	v_fma_f32 v167, v66, v167, v198
	v_fma_f32 v166, v66, v166, v214
	v_fma_f32 v199, -v65, v166, v199
	v_fma_f32 v215, v65, v167, v215
	v_fma_f32 v167, v66, v167, v199
	v_fma_f32 v166, v66, v166, v215
	v_fma_f32 v8, -v65, v166, v8
	v_fma_f32 v144, v65, v167, v144
	v_fma_f32 v167, v66, v167, v8
	v_fma_f32 v166, v66, v166, v144
	v_fma_f32 v9, -v65, v166, v9
	v_fma_f32 v145, v65, v167, v145
	v_fma_f32 v167, v66, v167, v9
	v_fma_f32 v166, v66, v166, v145
	v_fma_f32 v10, -v65, v166, v10
	v_fma_f32 v146, v65, v167, v146
	v_fma_f32 v167, v66, v167, v10
	v_fma_f32 v166, v66, v166, v146
	v_fma_f32 v11, -v65, v166, v11
	v_fma_f32 v147, v65, v167, v147
	v_fma_f32 v167, v66, v167, v11
	v_fma_f32 v166, v66, v166, v147
	v_fma_f32 v200, -v65, v166, v200
	v_fma_f32 v216, v65, v167, v216
	v_fma_f32 v167, v66, v167, v200
	v_fma_f32 v166, v66, v166, v216
	v_fma_f32 v201, -v65, v166, v201
	v_fma_f32 v217, v65, v167, v217
	v_fma_f32 v167, v66, v167, v201
	v_fma_f32 v166, v66, v166, v217
	v_fma_f32 v202, -v65, v166, v202
	v_fma_f32 v218, v65, v167, v218
	v_fma_f32 v167, v66, v167, v202
	v_fma_f32 v166, v66, v166, v218
	v_fma_f32 v203, -v65, v166, v203
	v_fma_f32 v219, v65, v167, v219
	v_fma_f32 v167, v66, v167, v203
	v_fma_f32 v166, v66, v166, v219
	v_fma_f32 v12, -v65, v166, v12
	v_fma_f32 v148, v65, v167, v148
	v_fma_f32 v167, v66, v167, v12
	v_fma_f32 v166, v66, v166, v148
	v_fma_f32 v13, -v65, v166, v13
	v_fma_f32 v149, v65, v167, v149
	v_fma_f32 v167, v66, v167, v13
	v_fma_f32 v166, v66, v166, v149
	v_fma_f32 v14, -v65, v166, v14
	v_fma_f32 v150, v65, v167, v150
	v_fma_f32 v167, v66, v167, v14
	v_fma_f32 v166, v66, v166, v150
	v_fma_f32 v15, -v65, v166, v15
	v_fma_f32 v151, v65, v167, v151
	v_fma_f32 v167, v66, v167, v15
	v_fma_f32 v166, v66, v166, v151
	v_fma_f32 v204, -v65, v166, v204
	v_fma_f32 v220, v65, v167, v220
	v_fma_f32 v167, v66, v167, v204
	v_fma_f32 v166, v66, v166, v220
	v_fma_f32 v205, -v65, v166, v205
	v_fma_f32 v221, v65, v167, v221
	v_fma_f32 v167, v66, v167, v205
	v_fma_f32 v166, v66, v166, v221
	v_fma_f32 v206, -v65, v166, v206
	v_fma_f32 v222, v65, v167, v222
	v_fma_f32 v167, v66, v167, v206
	v_fma_f32 v166, v66, v166, v222
	v_fma_f32 v207, -v65, v166, v207
	v_fma_f32 v223, v65, v167, v223
	v_fma_f32 v167, v66, v167, v207
	v_fma_f32 v166, v66, v166, v223
	ds_read_b128 v[228:231], v101 offset:32
	global_load_dwordx4 v[44:47], v[120:121], off
	global_load_dwordx4 v[40:43], v[122:123], off
	global_load_dwordx4 v[36:39], v[124:125], off
	global_load_dwordx4 v[32:35], v[126:127], off
	s_waitcnt vmcnt(7) lgkmcnt(0)
; #define LAS __attribute__((address_space(3)))
; template <bool PASS2>
; __device__ __forceinline__ void s5_tile(const Ctx& C, int T, int sb_lo, int sb_hi, LAS unsigned char* lds, int wave, int lane) {
;     ...
;         for (int gi = 0; gi < 4; ++gi) {
;             const int g = wave * 4 + gi, gnx = wave * 4 + ((gi + 1) & 3);
;             bfx8 bb[4], cm[4];
; #pragma unroll
;             for (int cb = 0; cb < 4; ++cb) { bb[cb] = bbn[cb]; bbn[cb] = *(const bfx8*)(BBt + ((size_t)(gnx * 128 + cb * 32 + tl)) * GN + 8 * hh); }
;             if (PASS2) {
; #pragma unroll
;                 for (int ks = 0; ks < 4; ++ks) { cm[ks] = cmn[ks]; cmn[ks] = *(const bfx8*)(CMt + ((size_t)(gnx * GN + fr)) * 128 + 32 * ks + 8 * kq); }
;             }
;             float s0ar = 0.f, s0ai = 0.f, s0br = 0.f, s0bi = 0.f;
;             if (sample) { const size_t o0 = ((size_t)(2 * sb) * NG + g) * NP + lane, o1 = o0 + (size_t)NG * NP;
;                 s0ar = C.in(2)[o0]; s0ai = C.in(3)[o0]; s0br = C.in(2)[o1]; s0bi = C.in(3)[o1]; }
;             const bfx8 a = *(const LAS bfx8*)(XU + tl * XU_STRIDE + 16 * gi + 8 * hh);
; #pragma unroll
;             for (int cb = 0; cb < 4; ++cb) {
;                 v16f acc;
; #pragma unroll
;                 for (int r = 0; r < 16; ++r) acc[r] = 0.f;
;                 acc = __builtin_amdgcn_mfma_f32_32x32x16_bf16(bb[cb], a, acc, 0, 0, 0);
; #pragma unroll
;                 for (int rg = 0; rg < 4; ++rg) { v2u w; w.x = cvt_pk_c(acc[4 * rg], acc[4 * rg + 1]); w.y = cvt_pk_c(acc[4 * rg + 2], acc[4 * rg + 3]);
;                     *(LAS v2u*)(BH + tl * BH_STRIDE + cb * 32 + 8 * rg + 4 * hh) = w; }
;             }
;             LDS_FENCE();
;             {
;                 unsigned bu[32];
; #pragma unroll
;                 for (int t = 0; t < 32; ++t) bu[t] = *(const LAS unsigned*)(BH + t * BH_STRIDE + 2 * lane);
;                 LDS_FENCE();
;                 float xr = sr[gi], xi = si[gi];
; #pragma unroll
;                 for (int t = 0; t < 32; ++t) {
;                     if (sample && t == 0) { xr = s0ar; xi = s0ai; }
;                     if (sample && t == 16) { xr = s0br; xi = s0bi; }
;                     const float nr = fmaf(lr[gi], xr, fmaf(-li[gi], xi, bf_lo(bu[t]))), ni = fmaf(lr[gi], xi, fmaf(li[gi], xr, bf_hi(bu[t])));
;                     xr = nr; xi = ni;
;                     if (PASS2) {
	v_mfma_f32_32x32x16_bf16 v[0:15], v[228:231], v[60:63], 0
	s_waitcnt vmcnt(6)
	v_mfma_f32_32x32x16_bf16 v[136:151], v[228:231], v[56:59], 0
	s_waitcnt vmcnt(5)
	v_mfma_f32_32x32x16_bf16 v[192:207], v[228:231], v[52:55], 0
	s_waitcnt vmcnt(4)
	v_mfma_f32_32x32x16_bf16 v[208:223], v[228:231], v[48:51], 0
	s_nop 11
	v_permlane32_swap_b32_e32 v0, v192
	v_permlane32_swap_b32_e32 v1, v193
	v_permlane32_swap_b32_e32 v2, v194
	v_permlane32_swap_b32_e32 v3, v195
	v_permlane32_swap_b32_e32 v4, v196
	v_permlane32_swap_b32_e32 v5, v197
	v_permlane32_swap_b32_e32 v6, v198
	v_permlane32_swap_b32_e32 v7, v199
	v_permlane32_swap_b32_e32 v8, v200
	v_permlane32_swap_b32_e32 v9, v201
	v_permlane32_swap_b32_e32 v10, v202
	v_permlane32_swap_b32_e32 v11, v203
	v_permlane32_swap_b32_e32 v12, v204
	v_permlane32_swap_b32_e32 v13, v205
	v_permlane32_swap_b32_e32 v14, v206
	v_permlane32_swap_b32_e32 v15, v207
	v_permlane32_swap_b32_e32 v136, v208
	v_permlane32_swap_b32_e32 v137, v209
	v_permlane32_swap_b32_e32 v138, v210
	v_permlane32_swap_b32_e32 v139, v211
	v_permlane32_swap_b32_e32 v140, v212
	v_permlane32_swap_b32_e32 v141, v213
	v_permlane32_swap_b32_e32 v142, v214
	v_permlane32_swap_b32_e32 v143, v215
	v_permlane32_swap_b32_e32 v144, v216
	v_permlane32_swap_b32_e32 v145, v217
	v_permlane32_swap_b32_e32 v146, v218
	v_permlane32_swap_b32_e32 v147, v219
	v_permlane32_swap_b32_e32 v148, v220
	v_permlane32_swap_b32_e32 v149, v221
	v_permlane32_swap_b32_e32 v150, v222
	v_permlane32_swap_b32_e32 v151, v223
	v_fma_f32 v0, -v71, v164, v0
	v_fma_f32 v136, v71, v165, v136
	v_fma_f32 v165, v68, v165, v0
	v_fma_f32 v164, v68, v164, v136
	v_fma_f32 v1, -v71, v164, v1
	v_fma_f32 v137, v71, v165, v137
	v_fma_f32 v165, v68, v165, v1
	v_fma_f32 v164, v68, v164, v137
	v_fma_f32 v2, -v71, v164, v2
	v_fma_f32 v138, v71, v165, v138
	v_fma_f32 v165, v68, v165, v2
	v_fma_f32 v164, v68, v164, v138
	v_fma_f32 v3, -v71, v164, v3
	v_fma_f32 v139, v71, v165, v139
	v_fma_f32 v165, v68, v165, v3
	v_fma_f32 v164, v68, v164, v139
	v_fma_f32 v192, -v71, v164, v192
	v_fma_f32 v208, v71, v165, v208
	v_fma_f32 v165, v68, v165, v192
	v_fma_f32 v164, v68, v164, v208
	v_fma_f32 v193, -v71, v164, v193
	v_fma_f32 v209, v71, v165, v209
	v_fma_f32 v165, v68, v165, v193
	v_fma_f32 v164, v68, v164, v209
	v_fma_f32 v194, -v71, v164, v194
	v_fma_f32 v210, v71, v165, v210
	v_fma_f32 v165, v68, v165, v194
	v_fma_f32 v164, v68, v164, v210
	v_fma_f32 v195, -v71, v164, v195
	v_fma_f32 v211, v71, v165, v211
	v_fma_f32 v165, v68, v165, v195
	v_fma_f32 v164, v68, v164, v211
	v_fma_f32 v4, -v71, v164, v4
	v_fma_f32 v140, v71, v165, v140
	v_fma_f32 v165, v68, v165, v4
	v_fma_f32 v164, v68, v164, v140
	v_fma_f32 v5, -v71, v164, v5
	v_fma_f32 v141, v71, v165, v141
	v_fma_f32 v165, v68, v165, v5
	v_fma_f32 v164, v68, v164, v141
	v_fma_f32 v6, -v71, v164, v6
	v_fma_f32 v142, v71, v165, v142
	v_fma_f32 v165, v68, v165, v6
	v_fma_f32 v164, v68, v164, v142
	v_fma_f32 v7, -v71, v164, v7
	v_fma_f32 v143, v71, v165, v143
	v_fma_f32 v165, v68, v165, v7
	v_fma_f32 v164, v68, v164, v143
	v_fma_f32 v196, -v71, v164, v196
	v_fma_f32 v212, v71, v165, v212
	v_fma_f32 v165, v68, v165, v196
	v_fma_f32 v164, v68, v164, v212
	v_fma_f32 v197, -v71, v164, v197
	v_fma_f32 v213, v71, v165, v213
	v_fma_f32 v165, v68, v165, v197
	v_fma_f32 v164, v68, v164, v213
	v_fma_f32 v198, -v71, v164, v198
	v_fma_f32 v214, v71, v165, v214
	v_fma_f32 v165, v68, v165, v198
	v_fma_f32 v164, v68, v164, v214
	v_fma_f32 v199, -v71, v164, v199
	v_fma_f32 v215, v71, v165, v215
	v_fma_f32 v165, v68, v165, v199
	v_fma_f32 v164, v68, v164, v215
	v_fma_f32 v8, -v71, v164, v8
	v_fma_f32 v144, v71, v165, v144
	v_fma_f32 v165, v68, v165, v8
	v_fma_f32 v164, v68, v164, v144
	v_fma_f32 v9, -v71, v164, v9
	v_fma_f32 v145, v71, v165, v145
	v_fma_f32 v165, v68, v165, v9
	v_fma_f32 v164, v68, v164, v145
	v_fma_f32 v10, -v71, v164, v10
	v_fma_f32 v146, v71, v165, v146
	v_fma_f32 v165, v68, v165, v10
	v_fma_f32 v164, v68, v164, v146
	v_fma_f32 v11, -v71, v164, v11
	v_fma_f32 v147, v71, v165, v147
	v_fma_f32 v165, v68, v165, v11
	v_fma_f32 v164, v68, v164, v147
	v_fma_f32 v200, -v71, v164, v200
	v_fma_f32 v216, v71, v165, v216
	v_fma_f32 v165, v68, v165, v200
	v_fma_f32 v164, v68, v164, v216
	v_fma_f32 v201, -v71, v164, v201
	v_fma_f32 v217, v71, v165, v217
	v_fma_f32 v165, v68, v165, v201
	v_fma_f32 v164, v68, v164, v217
	v_fma_f32 v202, -v71, v164, v202
	v_fma_f32 v218, v71, v165, v218
	v_fma_f32 v165, v68, v165, v202
	v_fma_f32 v164, v68, v164, v218
	v_fma_f32 v203, -v71, v164, v203
	v_fma_f32 v219, v71, v165, v219
	v_fma_f32 v165, v68, v165, v203
	v_fma_f32 v164, v68, v164, v219
	v_fma_f32 v12, -v71, v164, v12
	v_fma_f32 v148, v71, v165, v148
	v_fma_f32 v165, v68, v165, v12
	v_fma_f32 v164, v68, v164, v148
	v_fma_f32 v13, -v71, v164, v13
	v_fma_f32 v149, v71, v165, v149
	v_fma_f32 v165, v68, v165, v13
	v_fma_f32 v164, v68, v164, v149
	v_fma_f32 v14, -v71, v164, v14
	v_fma_f32 v150, v71, v165, v150
	v_fma_f32 v165, v68, v165, v14
	v_fma_f32 v164, v68, v164, v150
	v_fma_f32 v15, -v71, v164, v15
	v_fma_f32 v151, v71, v165, v151
	v_fma_f32 v165, v68, v165, v15
	v_fma_f32 v164, v68, v164, v151
	v_fma_f32 v204, -v71, v164, v204
	v_fma_f32 v220, v71, v165, v220
	v_fma_f32 v165, v68, v165, v204
	v_fma_f32 v164, v68, v164, v220
	v_fma_f32 v205, -v71, v164, v205
	v_fma_f32 v221, v71, v165, v221
	v_fma_f32 v165, v68, v165, v205
	v_fma_f32 v164, v68, v164, v221
	v_fma_f32 v206, -v71, v164, v206
	v_fma_f32 v222, v71, v165, v222
	v_fma_f32 v165, v68, v165, v206
	v_fma_f32 v164, v68, v164, v222
	v_fma_f32 v207, -v71, v164, v207
	v_fma_f32 v223, v71, v165, v223
	v_fma_f32 v165, v68, v165, v207
	v_fma_f32 v164, v68, v164, v223
	ds_read_b128 v[224:227], v101 offset:64
	global_load_dwordx4 v[60:63], v[128:129], off
	global_load_dwordx4 v[56:59], v[130:131], off
	global_load_dwordx4 v[52:55], v[132:133], off
	global_load_dwordx4 v[48:51], v[134:135], off
	s_waitcnt vmcnt(7) lgkmcnt(0)
; #define LAS __attribute__((address_space(3)))
; template <bool PASS2>
; __device__ __forceinline__ void s5_tile(const Ctx& C, int T, int sb_lo, int sb_hi, LAS unsigned char* lds, int wave, int lane) {
;     ...
;         for (int gi = 0; gi < 4; ++gi) {
;             const int g = wave * 4 + gi, gnx = wave * 4 + ((gi + 1) & 3);
;             bfx8 bb[4], cm[4];
; #pragma unroll
;             for (int cb = 0; cb < 4; ++cb) { bb[cb] = bbn[cb]; bbn[cb] = *(const bfx8*)(BBt + ((size_t)(gnx * 128 + cb * 32 + tl)) * GN + 8 * hh); }
;             if (PASS2) {
; #pragma unroll
;                 for (int ks = 0; ks < 4; ++ks) { cm[ks] = cmn[ks]; cmn[ks] = *(const bfx8*)(CMt + ((size_t)(gnx * GN + fr)) * 128 + 32 * ks + 8 * kq); }
;             }
;             float s0ar = 0.f, s0ai = 0.f, s0br = 0.f, s0bi = 0.f;
;             if (sample) { const size_t o0 = ((size_t)(2 * sb) * NG + g) * NP + lane, o1 = o0 + (size_t)NG * NP;
;                 s0ar = C.in(2)[o0]; s0ai = C.in(3)[o0]; s0br = C.in(2)[o1]; s0bi = C.in(3)[o1]; }
;             const bfx8 a = *(const LAS bfx8*)(XU + tl * XU_STRIDE + 16 * gi + 8 * hh);
; #pragma unroll
;             for (int cb = 0; cb < 4; ++cb) {
;                 v16f acc;
; #pragma unroll
;                 for (int r = 0; r < 16; ++r) acc[r] = 0.f;
;                 acc = __builtin_amdgcn_mfma_f32_32x32x16_bf16(bb[cb], a, acc, 0, 0, 0);
; #pragma unroll
;                 for (int rg = 0; rg < 4; ++rg) { v2u w; w.x = cvt_pk_c(acc[4 * rg], acc[4 * rg + 1]); w.y = cvt_pk_c(acc[4 * rg + 2], acc[4 * rg + 3]);
;                     *(LAS v2u*)(BH + tl * BH_STRIDE + cb * 32 + 8 * rg + 4 * hh) = w; }
;             }
;             LDS_FENCE();
;             {
;                 unsigned bu[32];
; #pragma unroll
;                 for (int t = 0; t < 32; ++t) bu[t] = *(const LAS unsigned*)(BH + t * BH_STRIDE + 2 * lane);
;                 LDS_FENCE();
;                 float xr = sr[gi], xi = si[gi];
; #pragma unroll
;                 for (int t = 0; t < 32; ++t) {
;                     if (sample && t == 0) { xr = s0ar; xi = s0ai; }
;                     if (sample && t == 16) { xr = s0br; xi = s0bi; }
;                     const float nr = fmaf(lr[gi], xr, fmaf(-li[gi], xi, bf_lo(bu[t]))), ni = fmaf(lr[gi], xi, fmaf(li[gi], xr, bf_hi(bu[t])));
;                     xr = nr; xi = ni;
;                     if (PASS2) {
	v_mfma_f32_32x32x16_bf16 v[0:15], v[224:227], v[44:47], 0
	s_waitcnt vmcnt(6)
	v_mfma_f32_32x32x16_bf16 v[136:151], v[224:227], v[40:43], 0
	s_waitcnt vmcnt(5)
	v_mfma_f32_32x32x16_bf16 v[192:207], v[224:227], v[36:39], 0
	s_waitcnt vmcnt(4)
	v_mfma_f32_32x32x16_bf16 v[208:223], v[224:227], v[32:35], 0
	s_nop 11
	v_permlane32_swap_b32_e32 v0, v192
	v_permlane32_swap_b32_e32 v1, v193
	v_permlane32_swap_b32_e32 v2, v194
	v_permlane32_swap_b32_e32 v3, v195
	v_permlane32_swap_b32_e32 v4, v196
	v_permlane32_swap_b32_e32 v5, v197
	v_permlane32_swap_b32_e32 v6, v198
	v_permlane32_swap_b32_e32 v7, v199
	v_permlane32_swap_b32_e32 v8, v200
	v_permlane32_swap_b32_e32 v9, v201
	v_permlane32_swap_b32_e32 v10, v202
	v_permlane32_swap_b32_e32 v11, v203
	v_permlane32_swap_b32_e32 v12, v204
	v_permlane32_swap_b32_e32 v13, v205
	v_permlane32_swap_b32_e32 v14, v206
	v_permlane32_swap_b32_e32 v15, v207
	v_permlane32_swap_b32_e32 v136, v208
	v_permlane32_swap_b32_e32 v137, v209
	v_permlane32_swap_b32_e32 v138, v210
	v_permlane32_swap_b32_e32 v139, v211
	v_permlane32_swap_b32_e32 v140, v212
	v_permlane32_swap_b32_e32 v141, v213
	v_permlane32_swap_b32_e32 v142, v214
	v_permlane32_swap_b32_e32 v143, v215
	v_permlane32_swap_b32_e32 v144, v216
	v_permlane32_swap_b32_e32 v145, v217
	v_permlane32_swap_b32_e32 v146, v218
	v_permlane32_swap_b32_e32 v147, v219
	v_permlane32_swap_b32_e32 v148, v220
	v_permlane32_swap_b32_e32 v149, v221
	v_permlane32_swap_b32_e32 v150, v222
	v_permlane32_swap_b32_e32 v151, v223
	v_fma_f32 v0, -v75, v162, v0
	v_fma_f32 v136, v75, v163, v136
	v_fma_f32 v163, v72, v163, v0
	v_fma_f32 v162, v72, v162, v136
	v_fma_f32 v1, -v75, v162, v1
	v_fma_f32 v137, v75, v163, v137
	v_fma_f32 v163, v72, v163, v1
	v_fma_f32 v162, v72, v162, v137
	v_fma_f32 v2, -v75, v162, v2
	v_fma_f32 v138, v75, v163, v138
	v_fma_f32 v163, v72, v163, v2
	v_fma_f32 v162, v72, v162, v138
	v_fma_f32 v3, -v75, v162, v3
	v_fma_f32 v139, v75, v163, v139
	v_fma_f32 v163, v72, v163, v3
	v_fma_f32 v162, v72, v162, v139
	v_fma_f32 v192, -v75, v162, v192
	v_fma_f32 v208, v75, v163, v208
	v_fma_f32 v163, v72, v163, v192
	v_fma_f32 v162, v72, v162, v208
	v_fma_f32 v193, -v75, v162, v193
	v_fma_f32 v209, v75, v163, v209
	v_fma_f32 v163, v72, v163, v193
	v_fma_f32 v162, v72, v162, v209
	v_fma_f32 v194, -v75, v162, v194
	v_fma_f32 v210, v75, v163, v210
	v_fma_f32 v163, v72, v163, v194
	v_fma_f32 v162, v72, v162, v210
	v_fma_f32 v195, -v75, v162, v195
	v_fma_f32 v211, v75, v163, v211
	v_fma_f32 v163, v72, v163, v195
	v_fma_f32 v162, v72, v162, v211
	v_fma_f32 v4, -v75, v162, v4
	v_fma_f32 v140, v75, v163, v140
	v_fma_f32 v163, v72, v163, v4
	v_fma_f32 v162, v72, v162, v140
	v_fma_f32 v5, -v75, v162, v5
	v_fma_f32 v141, v75, v163, v141
	v_fma_f32 v163, v72, v163, v5
	v_fma_f32 v162, v72, v162, v141
	v_fma_f32 v6, -v75, v162, v6
	v_fma_f32 v142, v75, v163, v142
	v_fma_f32 v163, v72, v163, v6
	v_fma_f32 v162, v72, v162, v142
	v_fma_f32 v7, -v75, v162, v7
	v_fma_f32 v143, v75, v163, v143
	v_fma_f32 v163, v72, v163, v7
	v_fma_f32 v162, v72, v162, v143
	v_fma_f32 v196, -v75, v162, v196
	v_fma_f32 v212, v75, v163, v212
	v_fma_f32 v163, v72, v163, v196
	v_fma_f32 v162, v72, v162, v212
	v_fma_f32 v197, -v75, v162, v197
	v_fma_f32 v213, v75, v163, v213
	v_fma_f32 v163, v72, v163, v197
	v_fma_f32 v162, v72, v162, v213
	v_fma_f32 v198, -v75, v162, v198
	v_fma_f32 v214, v75, v163, v214
	v_fma_f32 v163, v72, v163, v198
	v_fma_f32 v162, v72, v162, v214
	v_fma_f32 v199, -v75, v162, v199
	v_fma_f32 v215, v75, v163, v215
	v_fma_f32 v163, v72, v163, v199
	v_fma_f32 v162, v72, v162, v215
	v_fma_f32 v8, -v75, v162, v8
	v_fma_f32 v144, v75, v163, v144
	v_fma_f32 v163, v72, v163, v8
	v_fma_f32 v162, v72, v162, v144
	v_fma_f32 v9, -v75, v162, v9
	v_fma_f32 v145, v75, v163, v145
	v_fma_f32 v163, v72, v163, v9
	v_fma_f32 v162, v72, v162, v145
	v_fma_f32 v10, -v75, v162, v10
	v_fma_f32 v146, v75, v163, v146
	v_fma_f32 v163, v72, v163, v10
	v_fma_f32 v162, v72, v162, v146
	v_fma_f32 v11, -v75, v162, v11
	v_fma_f32 v147, v75, v163, v147
	v_fma_f32 v163, v72, v163, v11
	v_fma_f32 v162, v72, v162, v147
	v_fma_f32 v200, -v75, v162, v200
	v_fma_f32 v216, v75, v163, v216
	v_fma_f32 v163, v72, v163, v200
	v_fma_f32 v162, v72, v162, v216
	v_fma_f32 v201, -v75, v162, v201
	v_fma_f32 v217, v75, v163, v217
	v_fma_f32 v163, v72, v163, v201
	v_fma_f32 v162, v72, v162, v217
	v_fma_f32 v202, -v75, v162, v202
	v_fma_f32 v218, v75, v163, v218
	v_fma_f32 v163, v72, v163, v202
	v_fma_f32 v162, v72, v162, v218
	v_fma_f32 v203, -v75, v162, v203
	v_fma_f32 v219, v75, v163, v219
	v_fma_f32 v163, v72, v163, v203
	v_fma_f32 v162, v72, v162, v219
	v_fma_f32 v12, -v75, v162, v12
	v_fma_f32 v148, v75, v163, v148
	v_fma_f32 v163, v72, v163, v12
	v_fma_f32 v162, v72, v162, v148
	v_fma_f32 v13, -v75, v162, v13
	v_fma_f32 v149, v75, v163, v149
	v_fma_f32 v163, v72, v163, v13
	v_fma_f32 v162, v72, v162, v149
	v_fma_f32 v14, -v75, v162, v14
	v_fma_f32 v150, v75, v163, v150
	v_fma_f32 v163, v72, v163, v14
	v_fma_f32 v162, v72, v162, v150
	v_fma_f32 v15, -v75, v162, v15
	v_fma_f32 v151, v75, v163, v151
	v_fma_f32 v163, v72, v163, v15
	v_fma_f32 v162, v72, v162, v151
	v_fma_f32 v204, -v75, v162, v204
	v_fma_f32 v220, v75, v163, v220
	v_fma_f32 v163, v72, v163, v204
	v_fma_f32 v162, v72, v162, v220
	v_fma_f32 v205, -v75, v162, v205
	v_fma_f32 v221, v75, v163, v221
	v_fma_f32 v163, v72, v163, v205
	v_fma_f32 v162, v72, v162, v221
	v_fma_f32 v206, -v75, v162, v206
	v_fma_f32 v222, v75, v163, v222
	v_fma_f32 v163, v72, v163, v206
	v_fma_f32 v162, v72, v162, v222
	v_fma_f32 v207, -v75, v162, v207
	v_fma_f32 v223, v75, v163, v223
	v_fma_f32 v163, v72, v163, v207
	v_fma_f32 v162, v72, v162, v223
	ds_read_b128 v[228:231], v101 offset:96
	global_load_dwordx4 v[44:47], v[104:105], off
	global_load_dwordx4 v[40:43], v[106:107], off
	global_load_dwordx4 v[36:39], v[108:109], off
	global_load_dwordx4 v[32:35], v[110:111], off
	s_waitcnt vmcnt(7) lgkmcnt(0)
; #define LAS __attribute__((address_space(3)))
; template <bool PASS2>
; __device__ __forceinline__ void s5_tile(const Ctx& C, int T, int sb_lo, int sb_hi, LAS unsigned char* lds, int wave, int lane) {
;     ...
;         for (int gi = 0; gi < 4; ++gi) {
;             const int g = wave * 4 + gi, gnx = wave * 4 + ((gi + 1) & 3);
;             bfx8 bb[4], cm[4];
; #pragma unroll
;             for (int cb = 0; cb < 4; ++cb) { bb[cb] = bbn[cb]; bbn[cb] = *(const bfx8*)(BBt + ((size_t)(gnx * 128 + cb * 32 + tl)) * GN + 8 * hh); }
;             if (PASS2) {
; #pragma unroll
;                 for (int ks = 0; ks < 4; ++ks) { cm[ks] = cmn[ks]; cmn[ks] = *(const bfx8*)(CMt + ((size_t)(gnx * GN + fr)) * 128 + 32 * ks + 8 * kq); }
;             }
;             float s0ar = 0.f, s0ai = 0.f, s0br = 0.f, s0bi = 0.f;
;             if (sample) { const size_t o0 = ((size_t)(2 * sb) * NG + g) * NP + lane, o1 = o0 + (size_t)NG * NP;
;                 s0ar = C.in(2)[o0]; s0ai = C.in(3)[o0]; s0br = C.in(2)[o1]; s0bi = C.in(3)[o1]; }
;             const bfx8 a = *(const LAS bfx8*)(XU + tl * XU_STRIDE + 16 * gi + 8 * hh);
; #pragma unroll
;             for (int cb = 0; cb < 4; ++cb) {
;                 v16f acc;
; #pragma unroll
;                 for (int r = 0; r < 16; ++r) acc[r] = 0.f;
;                 acc = __builtin_amdgcn_mfma_f32_32x32x16_bf16(bb[cb], a, acc, 0, 0, 0);
; #pragma unroll
;                 for (int rg = 0; rg < 4; ++rg) { v2u w; w.x = cvt_pk_c(acc[4 * rg], acc[4 * rg + 1]); w.y = cvt_pk_c(acc[4 * rg + 2], acc[4 * rg + 3]);
;                     *(LAS v2u*)(BH + tl * BH_STRIDE + cb * 32 + 8 * rg + 4 * hh) = w; }
;             }
;             LDS_FENCE();
;             {
;                 unsigned bu[32];
; #pragma unroll
;                 for (int t = 0; t < 32; ++t) bu[t] = *(const LAS unsigned*)(BH + t * BH_STRIDE + 2 * lane);
;                 LDS_FENCE();
;                 float xr = sr[gi], xi = si[gi];
; #pragma unroll
;                 for (int t = 0; t < 32; ++t) {
;                     if (sample && t == 0) { xr = s0ar; xi = s0ai; }
;                     if (sample && t == 16) { xr = s0br; xi = s0bi; }
;                     const float nr = fmaf(lr[gi], xr, fmaf(-li[gi], xi, bf_lo(bu[t]))), ni = fmaf(lr[gi], xi, fmaf(li[gi], xr, bf_hi(bu[t])));
;                     xr = nr; xi = ni;
;                     if (PASS2) {
	v_mfma_f32_32x32x16_bf16 v[0:15], v[228:231], v[60:63], 0
	s_waitcnt vmcnt(6)
	v_mfma_f32_32x32x16_bf16 v[136:151], v[228:231], v[56:59], 0
	s_waitcnt vmcnt(5)
	v_mfma_f32_32x32x16_bf16 v[192:207], v[228:231], v[52:55], 0
	s_waitcnt vmcnt(4)
	v_mfma_f32_32x32x16_bf16 v[208:223], v[228:231], v[48:51], 0
	s_nop 11
	v_permlane32_swap_b32_e32 v0, v192
	v_permlane32_swap_b32_e32 v1, v193
	v_permlane32_swap_b32_e32 v2, v194
	v_permlane32_swap_b32_e32 v3, v195
	v_permlane32_swap_b32_e32 v4, v196
	v_permlane32_swap_b32_e32 v5, v197
	v_permlane32_swap_b32_e32 v6, v198
	v_permlane32_swap_b32_e32 v7, v199
	v_permlane32_swap_b32_e32 v8, v200
	v_permlane32_swap_b32_e32 v9, v201
	v_permlane32_swap_b32_e32 v10, v202
	v_permlane32_swap_b32_e32 v11, v203
	v_permlane32_swap_b32_e32 v12, v204
	v_permlane32_swap_b32_e32 v13, v205
	v_permlane32_swap_b32_e32 v14, v206
	v_permlane32_swap_b32_e32 v15, v207
	v_permlane32_swap_b32_e32 v136, v208
	v_permlane32_swap_b32_e32 v137, v209
	v_permlane32_swap_b32_e32 v138, v210
	v_permlane32_swap_b32_e32 v139, v211
	v_permlane32_swap_b32_e32 v140, v212
	v_permlane32_swap_b32_e32 v141, v213
	v_permlane32_swap_b32_e32 v142, v214
	v_permlane32_swap_b32_e32 v143, v215
	v_permlane32_swap_b32_e32 v144, v216
	v_permlane32_swap_b32_e32 v145, v217
	v_permlane32_swap_b32_e32 v146, v218
	v_permlane32_swap_b32_e32 v147, v219
	v_permlane32_swap_b32_e32 v148, v220
	v_permlane32_swap_b32_e32 v149, v221
	v_permlane32_swap_b32_e32 v150, v222
	v_permlane32_swap_b32_e32 v151, v223
	v_fma_f32 v0, -v79, v160, v0
	v_fma_f32 v136, v79, v161, v136
	v_fma_f32 v161, v76, v161, v0
	v_fma_f32 v160, v76, v160, v136
	v_fma_f32 v1, -v79, v160, v1
	v_fma_f32 v137, v79, v161, v137
	v_fma_f32 v161, v76, v161, v1
	v_fma_f32 v160, v76, v160, v137
	v_fma_f32 v2, -v79, v160, v2
	v_fma_f32 v138, v79, v161, v138
	v_fma_f32 v161, v76, v161, v2
	v_fma_f32 v160, v76, v160, v138
	v_fma_f32 v3, -v79, v160, v3
	v_fma_f32 v139, v79, v161, v139
	v_fma_f32 v161, v76, v161, v3
	v_fma_f32 v160, v76, v160, v139
	v_fma_f32 v192, -v79, v160, v192
	v_fma_f32 v208, v79, v161, v208
	v_fma_f32 v161, v76, v161, v192
	v_fma_f32 v160, v76, v160, v208
	v_fma_f32 v193, -v79, v160, v193
	v_fma_f32 v209, v79, v161, v209
	v_fma_f32 v161, v76, v161, v193
	v_fma_f32 v160, v76, v160, v209
	v_fma_f32 v194, -v79, v160, v194
	v_fma_f32 v210, v79, v161, v210
	v_fma_f32 v161, v76, v161, v194
	v_fma_f32 v160, v76, v160, v210
	v_fma_f32 v195, -v79, v160, v195
	v_fma_f32 v211, v79, v161, v211
	v_fma_f32 v161, v76, v161, v195
	v_fma_f32 v160, v76, v160, v211
	v_fma_f32 v4, -v79, v160, v4
	v_fma_f32 v140, v79, v161, v140
	v_fma_f32 v161, v76, v161, v4
	v_fma_f32 v160, v76, v160, v140
	v_fma_f32 v5, -v79, v160, v5
	v_fma_f32 v141, v79, v161, v141
	v_fma_f32 v161, v76, v161, v5
	v_fma_f32 v160, v76, v160, v141
	v_fma_f32 v6, -v79, v160, v6
	v_fma_f32 v142, v79, v161, v142
	v_fma_f32 v161, v76, v161, v6
	v_fma_f32 v160, v76, v160, v142
	v_fma_f32 v7, -v79, v160, v7
	v_fma_f32 v143, v79, v161, v143
	v_fma_f32 v161, v76, v161, v7
	v_fma_f32 v160, v76, v160, v143
	v_fma_f32 v196, -v79, v160, v196
	v_fma_f32 v212, v79, v161, v212
	v_fma_f32 v161, v76, v161, v196
	v_fma_f32 v160, v76, v160, v212
	v_fma_f32 v197, -v79, v160, v197
	v_fma_f32 v213, v79, v161, v213
	v_fma_f32 v161, v76, v161, v197
	v_fma_f32 v160, v76, v160, v213
	v_fma_f32 v198, -v79, v160, v198
	v_fma_f32 v214, v79, v161, v214
	v_fma_f32 v161, v76, v161, v198
	v_fma_f32 v160, v76, v160, v214
	v_fma_f32 v199, -v79, v160, v199
	v_fma_f32 v215, v79, v161, v215
	v_fma_f32 v161, v76, v161, v199
	v_fma_f32 v160, v76, v160, v215
	v_fma_f32 v8, -v79, v160, v8
	v_fma_f32 v144, v79, v161, v144
	v_fma_f32 v161, v76, v161, v8
	v_fma_f32 v160, v76, v160, v144
	v_fma_f32 v9, -v79, v160, v9
	v_fma_f32 v145, v79, v161, v145
	v_fma_f32 v161, v76, v161, v9
	v_fma_f32 v160, v76, v160, v145
	v_fma_f32 v10, -v79, v160, v10
	v_fma_f32 v146, v79, v161, v146
	v_fma_f32 v161, v76, v161, v10
	v_fma_f32 v160, v76, v160, v146
	v_fma_f32 v11, -v79, v160, v11
	v_fma_f32 v147, v79, v161, v147
	v_fma_f32 v161, v76, v161, v11
	v_fma_f32 v160, v76, v160, v147
	v_fma_f32 v200, -v79, v160, v200
	v_fma_f32 v216, v79, v161, v216
	v_fma_f32 v161, v76, v161, v200
	v_fma_f32 v160, v76, v160, v216
	v_fma_f32 v201, -v79, v160, v201
	v_fma_f32 v217, v79, v161, v217
	v_fma_f32 v161, v76, v161, v201
	v_fma_f32 v160, v76, v160, v217
	v_fma_f32 v202, -v79, v160, v202
	v_fma_f32 v218, v79, v161, v218
	v_fma_f32 v161, v76, v161, v202
	v_fma_f32 v160, v76, v160, v218
	v_fma_f32 v203, -v79, v160, v203
	v_fma_f32 v219, v79, v161, v219
	v_fma_f32 v161, v76, v161, v203
	v_fma_f32 v160, v76, v160, v219
	v_fma_f32 v12, -v79, v160, v12
	v_fma_f32 v148, v79, v161, v148
	v_fma_f32 v161, v76, v161, v12
	v_fma_f32 v160, v76, v160, v148
	v_fma_f32 v13, -v79, v160, v13
	v_fma_f32 v149, v79, v161, v149
	v_fma_f32 v161, v76, v161, v13
	v_fma_f32 v160, v76, v160, v149
	v_fma_f32 v14, -v79, v160, v14
	v_fma_f32 v150, v79, v161, v150
	v_fma_f32 v161, v76, v161, v14
	v_fma_f32 v160, v76, v160, v150
	v_fma_f32 v15, -v79, v160, v15
	v_fma_f32 v151, v79, v161, v151
	v_fma_f32 v161, v76, v161, v15
	v_fma_f32 v160, v76, v160, v151
	v_fma_f32 v204, -v79, v160, v204
	v_fma_f32 v220, v79, v161, v220
	v_fma_f32 v161, v76, v161, v204
	v_fma_f32 v160, v76, v160, v220
	v_fma_f32 v205, -v79, v160, v205
	v_fma_f32 v221, v79, v161, v221
	v_fma_f32 v161, v76, v161, v205
	v_fma_f32 v160, v76, v160, v221
	v_fma_f32 v206, -v79, v160, v206
	v_fma_f32 v222, v79, v161, v222
	v_fma_f32 v161, v76, v161, v206
	v_fma_f32 v160, v76, v160, v222
	v_fma_f32 v207, -v79, v160, v207
	v_fma_f32 v223, v79, v161, v223
	v_fma_f32 v161, v76, v161, v207
	v_fma_f32 v160, v76, v160, v223
	s_cmp_lg_u32 s33, 0
	s_cbranch_scc1 .Lmy_p5_nost
	s_load_dwordx2 s[98:99], s[80:81], 0x110
	v_and_b32_e32 v152, 63, v81
	v_lshlrev_b32_e32 v152, 3, v152
	v_lshl_add_u32 v152, s42, 11, v152
	v_lshl_add_u32 v152, s25, 9, v152
	v_add_u32_e32 v152, 0x2a68000, v152
	v_mov_b32_e32 v153, 0
	s_waitcnt lgkmcnt(0)
	v_lshl_add_u64 v[152:153], s[98:99], 0, v[152:153]
	global_store_dwordx2 v[152:153], v[166:167], off
	global_store_dwordx2 v[152:153], v[164:165], off offset:512
	global_store_dwordx2 v[152:153], v[162:163], off offset:1024
	global_store_dwordx2 v[152:153], v[160:161], off offset:1536
.Lmy_p5_nost:
	s_add_i32 s25, s25, 32
	s_cmpk_lg_i32 s25, 0x80
	s_cbranch_scc0 .LBB0_599

; #define LAS __attribute__((address_space(3)))
; #define FTID const int ftid_ = fresh_tid()
; #define WAVE (__builtin_amdgcn_readfirstlane(ftid_ >> 6))
; template <bool PASS2>
; __device__ __forceinline__ void s5_tile(const Ctx& C, int T, int sb_lo, int sb_hi, LAS unsigned char* lds, int wave, int lane) {
;     const bool sample = (T == NTILE - 1);
;     const int r0 = T * 128;
;     LAS bf16* XU = (LAS bf16*)(lds + wave * S5W_BYTES);
;     LAS bf16* BH = XU + 32 * XU_STRIDE;
;     const int tl = lane & 31, hh = lane >> 5, fr = lane & 15, kq = lane >> 4, xrow = lane >> 3, xpart = lane & 7;
;     const float* LAM = C.LAM();
;     const bf16* Zb = C.Z() + (size_t)1024 + 64 * wave;
;     float sr[4], si[4], lr[4], li[4], dsk[4];
; __global__ void __launch_bounds__(NTHREADS, 2) fwd_kernel(Args args) {
;     ...
;     { FTID; const bool swap0 = GSZ > 128;
;       for (int T = BX; T < NTILE - 1; T += GSZ) { if (swap0 && T == 0) continue; s5_tile<true>(C, T, 0, 4, lds, WAVE, LANE); }
;       if (swap0 && BX == 128) s5_tile<true>(C, 0, 0, 4, lds, WAVE, LANE);
;       if (BX >= 1 && BX <= 4) s5_tile<true>(C, NTILE - 1, BX - 1, BX, lds, WAVE, LANE);
.LBB0_656:
	s_or_b64 exec, exec, s[8:9]
	v_mov_b32_e32 v160, v182
	s_cmpk_gt_i32 s94, 0x80
	s_waitcnt lgkmcnt(0)
	v_cndmask_b32_e64 v0, 0, 1, s[10:11]
	s_barrier
	s_cselect_b64 s[52:53], -1, 0
	v_cmp_ne_u32_e64 s[8:9], 1, v0
	s_andn2_b64 vcc, exec, s[10:11]
	v_bfe_u32 v162, v160, 3, 3
	v_bfe_u32 v161, v160, 4, 2
	v_and_b32_e32 v96, 48, v160
	s_cbranch_vccnz .LBB0_673
	v_and_b32_e32 v98, 63, v160
	v_and_b32_e32 v97, 31, v160
	v_and_b32_e32 v99, 15, v160
	v_bfe_u32 v1, v160, 5, 1
	v_and_b32_e32 v2, 7, v160
	v_lshlrev_b32_e32 v0, 3, v161
	v_or_b32_e32 v103, 0x800, v98
	v_or_b32_e32 v105, 0x1000, v98
	v_or_b32_e32 v163, 0x1800, v98
	v_mov_b32_e32 v101, 0
	v_lshlrev_b32_e32 v102, 3, v2
	v_lshlrev_b32_e32 v104, 3, v1
	v_lshlrev_b32_e32 v164, 4, v2
	v_mul_u32_u24_e32 v165, 0x90, v97
	v_lshlrev_b32_e32 v166, 4, v1
	v_mul_u32_u24_e32 v167, 0x110, v97
	v_lshlrev_b32_e32 v168, 2, v98
	v_mul_u32_u24_e32 v169, 0x90, v162
	v_mul_u32_u24_e32 v170, 0x240, v161
	v_mul_u32_u24_e32 v171, 0x110, v99
	v_lshl_or_b32 v172, s33, 7, v162
	s_lshl_b32 s42, s94, 7
	s_mov_b32 s55, 0
	s_mov_b64 s[56:57], 0x2b00000
	s_mov_b64 s[58:59], 0xb200800
	s_movk_i32 s43, 0xc00
	s_mov_b64 s[60:61], 0x2a00000
	v_mul_i32_i24_e32 v106, 0xffffff00, v99
	v_lshl_add_u32 v106, v98, 4, v106
	s_mov_b32 s47, 0x11300000
	s_mov_b32 s74, 0x8080000
	s_mov_b32 s75, 0x8084000
	s_mov_b32 s76, s33
	s_mov_b32 s98, 0
	s_mov_b32 s99, 0
	s_mov_b32 s77, s33
	s_branch .LBB0_659

; template <bool PASS2>
; __device__ __forceinline__ void s5_tile(const Ctx& C, int T, int sb_lo, int sb_hi, LAS unsigned char* lds, int wave, int lane) {
;     ...
;     v4u xn[4];
;     {
;         const int sb0 = sb_lo;
; #pragma unroll
;         for (int i = 0; i < 4; ++i) xn[i] = *(const v4u*)(Zb + (size_t)(r0 + 32 * sb0 + xrow + 8 * i) * DIN + 8 * xpart);
;     }
;     const bf16* BBt = C.BB(); const bf16* CMt = C.CM();
;     bfx8 bbn[4], cmn[4];
; #pragma unroll
;     for (int cb = 0; cb < 4; ++cb) bbn[cb] = *(const bfx8*)(BBt + ((size_t)(wave * 4 * 128 + cb * 32 + tl)) * GN + 8 * hh);
;     if (PASS2) {
; #pragma unroll
;         for (int ks = 0; ks < 4; ++ks) cmn[ks] = *(const bfx8*)(CMt + ((size_t)(wave * 4 * GN + fr)) * 128 + 32 * ks + 8 * kq);
;     }
;     for (int sb = sb_lo; sb < sb_hi; ++sb) {
.LBB0_665:
	s_cmp_eq_u32 s99, 0
	s_cbranch_scc1 .Lmy_p6_nost
	s_load_dwordx2 s[12:13], s[80:81], 0x110
	s_sub_i32 s10, s99, 32
	s_lshl_b32 s10, s10, 9
	s_lshl_b32 s11, s67, 11
	s_add_i32 s10, s10, s11
	s_add_i32 s10, s10, 0x2a68000
	v_lshlrev_b32_e32 v250, 3, v98
	v_add_u32_e32 v250, s10, v250
	v_mov_b32_e32 v251, 0
	s_waitcnt lgkmcnt(0)
	v_lshl_add_u64 v[250:251], s[12:13], 0, v[250:251]
	global_load_dword v112, v[250:251], off
	global_load_dword v114, v[250:251], off offset:4
	global_load_dword v113, v[250:251], off offset:512
	global_load_dword v115, v[250:251], off offset:516
	global_load_dword v108, v[250:251], off offset:1024
	global_load_dword v110, v[250:251], off offset:1028
	global_load_dword v109, v[250:251], off offset:1536
	global_load_dword v111, v[250:251], off offset:1540
	s_waitcnt vmcnt(0)
.Lmy_p6_nost:
	s_load_dwordx2 s[12:13], s[0:1], 0x110
	s_mul_i32 s0, s67, 0x3400
	s_ashr_i32 s73, s72, 31
	s_add_i32 s3, s0, 0
	s_lshl_b64 s[10:11], s[72:73], 1
	s_waitcnt lgkmcnt(0)
	s_add_u32 s0, s12, s10
	s_addc_u32 s1, s13, s11
	v_lshlrev_b32_e32 v100, 1, v102
	s_waitcnt vmcnt(3)
	v_lshl_or_b32 v12, s77, 7, v162
	v_add_u32_e32 v12, s99, v12
	v_lshl_add_u64 v[8:9], s[0:1], 0, v[100:101]
	v_lshl_add_u64 v[116:117], v[8:9], 0, s[58:59]
	v_or_b32_e32 v10, 8, v12
	v_mad_i64_i32 v[8:9], s[0:1], v12, s43, v[116:117]
	v_mad_i64_i32 v[10:11], s[0:1], v10, s43, v[116:117]
	global_load_dwordx4 v[16:19], v[8:9], off
	global_load_dwordx4 v[20:23], v[10:11], off
	v_or_b32_e32 v8, 16, v12
	v_or_b32_e32 v10, 24, v12
	v_mad_i64_i32 v[8:9], s[0:1], v8, s43, v[116:117]
	v_mad_i64_i32 v[10:11], s[0:1], v10, s43, v[116:117]
	s_mov_b64 s[0:1], s[80:81]
	global_load_dwordx4 v[24:27], v[8:9], off
	global_load_dwordx4 v[28:31], v[10:11], off
	s_mov_b64 s[12:13], s[80:81]
	s_load_dwordx2 s[0:1], s[0:1], 0x110
	s_load_dwordx2 s[12:13], s[12:13], 0x110
	v_and_b32_e32 v8, 1, v160
	v_lshlrev_b32_e32 v8, 4, v8
	v_add_u32_e32 v8, 0x48000, v8
	v_mov_b32_e32 v9, v101
	s_waitcnt lgkmcnt(0)
	v_lshl_add_u64 v[8:9], s[0:1], 0, v[8:9]
	v_lshlrev_b64 v[6:7], 8, v[6:7]
	s_add_u32 s0, s12, 0x2aa1000
	s_addc_u32 s1, s13, 0
	v_lshl_add_u64 v[10:11], s[0:1], 0, v[6:7]
	v_ashrrev_i32_e32 v107, 31, v106
	v_lshl_add_u64 v[10:11], v[10:11], 0, v[106:107]
	global_load_dwordx4 v[32:35], v[10:11], off offset:3072
	global_load_dwordx4 v[36:39], v[10:11], off offset:2048
	global_load_dwordx4 v[40:43], v[10:11], off offset:1024
	global_load_dwordx4 v[44:47], v[10:11], off
	v_bfe_u32 v231, v160, 1, 5
	v_lshl_or_b32 v10, s67, 9, v231
	v_or_b32_e32 v12, 0x60, v10
	s_waitcnt vmcnt(9)
	v_ashrrev_i32_e32 v13, 31, v12
	v_lshl_add_u64 v[8:9], v[8:9], 0, s[60:61]
	v_lshlrev_b64 v[12:13], 5, v[12:13]
	v_lshl_add_u64 v[118:119], v[8:9], 0, v[12:13]
	v_or_b32_e32 v12, 64, v10
	v_ashrrev_i32_e32 v13, 31, v12
	v_lshlrev_b64 v[12:13], 5, v[12:13]
	v_lshl_add_u64 v[120:121], v[8:9], 0, v[12:13]
	v_or_b32_e32 v12, 32, v10
	v_ashrrev_i32_e32 v13, 31, v12
	v_lshlrev_b64 v[12:13], 5, v[12:13]
	v_ashrrev_i32_e32 v11, 31, v10
	v_lshl_add_u64 v[122:123], v[8:9], 0, v[12:13]
	v_lshlrev_b64 v[10:11], 5, v[10:11]
	global_load_dwordx4 v[64:67], v[118:119], off
	global_load_dwordx4 v[68:71], v[120:121], off
	v_lshl_add_u64 v[124:125], v[8:9], 0, v[10:11]
	global_load_dwordx4 v[72:75], v[122:123], off
	global_load_dwordx4 v[76:79], v[124:125], off
	v_lshl_or_b32 v12, s64, 7, v231
	v_ashrrev_i32_e32 v13, 31, v12
	s_waitcnt vmcnt(12)
	v_lshlrev_b64 v[14:15], 5, v[12:13]
	v_lshl_add_u64 v[126:127], v[8:9], 0, v[14:15]
	v_or_b32_e32 v14, 32, v12
	v_ashrrev_i32_e32 v15, 31, v14
	v_lshlrev_b64 v[14:15], 5, v[14:15]
	v_lshl_add_u64 v[10:11], s[0:1], 0, v[106:107]
	v_lshl_add_u64 v[128:129], v[8:9], 0, v[14:15]
	v_or_b32_e32 v14, 64, v12
	v_or_b32_e32 v12, 0x60, v12
	v_lshlrev_b64 v[4:5], 8, v[4:5]
	v_ashrrev_i32_e32 v13, 31, v12
	v_lshl_add_u64 v[134:135], v[10:11], 0, v[4:5]
	v_lshl_or_b32 v4, s66, 7, v231
	v_lshlrev_b64 v[12:13], 5, v[12:13]
	v_ashrrev_i32_e32 v5, 31, v4
	v_lshl_add_u64 v[132:133], v[8:9], 0, v[12:13]
	v_lshlrev_b64 v[12:13], 5, v[4:5]
	v_lshl_add_u64 v[136:137], v[8:9], 0, v[12:13]
	v_or_b32_e32 v12, 32, v4
	v_ashrrev_i32_e32 v13, 31, v12
	v_lshlrev_b64 v[12:13], 5, v[12:13]
	v_lshl_add_u64 v[138:139], v[8:9], 0, v[12:13]
	v_or_b32_e32 v12, 64, v4
	v_or_b32_e32 v4, 0x60, v4
	v_lshlrev_b64 v[2:3], 8, v[2:3]
	v_ashrrev_i32_e32 v5, 31, v4
	v_lshl_add_u64 v[144:145], v[10:11], 0, v[2:3]
	v_lshl_or_b32 v2, s68, 7, v231
	v_lshlrev_b64 v[4:5], 5, v[4:5]
	v_ashrrev_i32_e32 v3, 31, v2
	v_lshl_add_u64 v[142:143], v[8:9], 0, v[4:5]
	v_lshlrev_b64 v[4:5], 5, v[2:3]
	v_lshl_add_u64 v[146:147], v[8:9], 0, v[4:5]
	v_or_b32_e32 v4, 32, v2
	v_ashrrev_i32_e32 v5, 31, v4
	v_lshlrev_b64 v[4:5], 5, v[4:5]
	v_lshl_add_u64 v[148:149], v[8:9], 0, v[4:5]
	v_or_b32_e32 v4, 64, v2
	v_or_b32_e32 v2, 0x60, v2
	v_ashrrev_i32_e32 v15, 31, v14
	v_ashrrev_i32_e32 v13, 31, v12
	v_ashrrev_i32_e32 v5, 31, v4
	v_ashrrev_i32_e32 v3, 31, v2
	v_add_u32_e32 v48, s3, v164
	v_lshl_add_u32 v49, v99, 1, s3
	v_add_u32_e32 v50, s3, v165
	v_add_u32_e32 v51, s3, v167
	v_add_u32_e32 v52, s3, v96
	v_lshlrev_b64 v[14:15], 5, v[14:15]
	v_lshlrev_b64 v[12:13], 5, v[12:13]
	v_lshlrev_b64 v[4:5], 5, v[4:5]
	v_lshlrev_b64 v[2:3], 5, v[2:3]
	v_lshlrev_b64 v[0:1], 8, v[0:1]
	v_add_u32_e32 v107, s3, v168
	v_lshl_add_u64 v[130:131], v[8:9], 0, v[14:15]
	v_lshl_add_u64 v[140:141], v[8:9], 0, v[12:13]
	v_lshl_add_u64 v[150:151], v[8:9], 0, v[4:5]
	v_lshl_add_u64 v[152:153], v[8:9], 0, v[2:3]
	v_lshl_add_u64 v[154:155], v[10:11], 0, v[0:1]
	v_lshl_add_u64 v[156:157], v[10:11], 0, v[6:7]
	s_mov_b32 s14, s99
	v_add_u32_e32 v192, v50, v166
	v_add_u32_e32 v193, v51, v104
	v_add_u32_e32 v194, v52, v171
	v_add_u32_e32 v195, v49, v170
	v_add_u32_e32 v196, v48, v169
	s_mul_i32 s15, s98, 3
	s_branch .LBB0_667
; template <bool PASS2>
; __device__ __forceinline__ void s5_tile(const Ctx& C, int T, int sb_lo, int sb_hi, LAS unsigned char* lds, int wave, int lane) {
;     ...
;     for (int sb = sb_lo; sb < sb_hi; ++sb) {
;         const int rb0 = r0 + 32 * sb;
; #pragma unroll
;         for (int i = 0; i < 4; ++i) *(LAS v4u*)(XU + (xrow + 8 * i) * XU_STRIDE + 8 * xpart) = xn[i];
;         if (sb + 1 < sb_hi) {
; #pragma unroll
;             for (int i = 0; i < 4; ++i) xn[i] = *(const v4u*)(Zb + (size_t)(rb0 + 32 + xrow + 8 * i) * DIN + 8 * xpart);
;         }
;         LDS_FENCE();
; #pragma unroll
;         for (int gi = 0; gi < 4; ++gi) {
;             const int g = wave * 4 + gi, gnx = wave * 4 + ((gi + 1) & 3);
;             bfx8 bb[4], cm[4];
; #pragma unroll
;             for (int cb = 0; cb < 4; ++cb) { bb[cb] = bbn[cb]; bbn[cb] = *(const bfx8*)(BBt + ((size_t)(gnx * 128 + cb * 32 + tl)) * GN + 8 * hh); }
;             if (PASS2) {
; #pragma unroll
;                 for (int ks = 0; ks < 4; ++ks) { cm[ks] = cmn[ks]; cmn[ks] = *(const bfx8*)(CMt + ((size_t)(gnx * GN + fr)) * 128 + 32 * ks + 8 * kq); }
;             }
;             float s0ar = 0.f, s0ai = 0.f, s0br = 0.f, s0bi = 0.f;
;             if (sample) { const size_t o0 = ((size_t)(2 * sb) * NG + g) * NP + lane, o1 = o0 + (size_t)NG * NP;
;                 s0ar = C.in(2)[o0]; s0ai = C.in(3)[o0]; s0br = C.in(2)[o1]; s0bi = C.in(3)[o1]; }
;             const bfx8 a = *(const LAS bfx8*)(XU + tl * XU_STRIDE + 16 * gi + 8 * hh);
; #pragma unroll
;             for (int cb = 0; cb < 4; ++cb) {
;                 v16f acc;
; #pragma unroll
;                 for (int r = 0; r < 16; ++r) acc[r] = 0.f;
;                 acc = __builtin_amdgcn_mfma_f32_32x32x16_bf16(bb[cb], a, acc, 0, 0, 0);
; #pragma unroll
;                 for (int rg = 0; rg < 4; ++rg) { v2u w; w.x = cvt_pk_c(acc[4 * rg], acc[4 * rg + 1]); w.y = cvt_pk_c(acc[4 * rg + 2], acc[4 * rg + 3]);
;                     *(LAS v2u*)(BH + tl * BH_STRIDE + cb * 32 + 8 * rg + 4 * hh) = w; }
;             }
;             LDS_FENCE();
;             {
;                 unsigned bu[32];
; #pragma unroll
;                 for (int t = 0; t < 32; ++t) bu[t] = *(const LAS unsigned*)(BH + t * BH_STRIDE + 2 * lane);
;                 LDS_FENCE();
;                 float xr = sr[gi], xi = si[gi];
; #pragma unroll
;                 for (int t = 0; t < 32; ++t) {
.LBB0_666:
	s_waitcnt lgkmcnt(0)
	global_load_dwordx4 v[92:95], v[126:127], off
	global_load_dwordx4 v[88:91], v[128:129], off
	global_load_dwordx4 v[84:87], v[130:131], off
	global_load_dwordx4 v[80:83], v[132:133], off
	ds_read_b128 v[250:253], v192
	global_load_dwordx4 v[60:63], v[134:135], off
	global_load_dwordx4 v[56:59], v[134:135], off offset:1024
	global_load_dwordx4 v[48:51], v[134:135], off offset:2048
	global_load_dwordx4 v[52:55], v[134:135], off offset:3072
	s_waitcnt vmcnt(8) lgkmcnt(0)
	v_mfma_f32_32x32x16_bf16 v[0:15], v[250:253], v[76:79], 0
	v_mfma_f32_32x32x16_bf16 v[214:229], v[250:253], v[72:75], 0
	s_mov_b64 s[0:1], s[80:81]
	s_add_i32 s14, s14, 32
	s_add_i32 s15, s15, 1
	s_cmpk_eq_i32 s15, 4
	v_mfma_f32_32x32x16_bf16 v[234:249], v[250:253], v[68:71], 0
	v_mfma_f32_32x32x16_bf16 v[198:213], v[250:253], v[64:67], 0
	s_nop 11
	v_permlane32_swap_b32_e32 v0, v234
	v_permlane32_swap_b32_e32 v1, v235
	v_permlane32_swap_b32_e32 v2, v236
	v_permlane32_swap_b32_e32 v3, v237
	v_permlane32_swap_b32_e32 v4, v238
	v_permlane32_swap_b32_e32 v5, v239
	v_permlane32_swap_b32_e32 v6, v240
	v_permlane32_swap_b32_e32 v7, v241
	v_permlane32_swap_b32_e32 v8, v242
	v_permlane32_swap_b32_e32 v9, v243
	v_permlane32_swap_b32_e32 v10, v244
	v_permlane32_swap_b32_e32 v11, v245
	v_permlane32_swap_b32_e32 v12, v246
	v_permlane32_swap_b32_e32 v13, v247
	v_permlane32_swap_b32_e32 v14, v248
	v_permlane32_swap_b32_e32 v15, v249
	v_permlane32_swap_b32_e32 v214, v198
	v_permlane32_swap_b32_e32 v215, v199
	v_permlane32_swap_b32_e32 v216, v200
	v_permlane32_swap_b32_e32 v217, v201
	v_permlane32_swap_b32_e32 v218, v202
	v_permlane32_swap_b32_e32 v219, v203
	v_permlane32_swap_b32_e32 v220, v204
	v_permlane32_swap_b32_e32 v221, v205
	v_permlane32_swap_b32_e32 v222, v206
	v_permlane32_swap_b32_e32 v223, v207
	v_permlane32_swap_b32_e32 v224, v208
	v_permlane32_swap_b32_e32 v225, v209
	v_permlane32_swap_b32_e32 v226, v210
	v_permlane32_swap_b32_e32 v227, v211
	v_permlane32_swap_b32_e32 v228, v212
	v_permlane32_swap_b32_e32 v229, v213
	v_fma_f32 v0, -v174, v112, v0
	v_fma_f32 v214, v174, v114, v214
	v_fma_f32 v114, v173, v114, v0
	v_fma_f32 v112, v173, v112, v214
	v_cvt_pk_bf16_f32 v197, v114, v112
	ds_write_b32 v107, v197 offset:4608
	v_fma_f32 v1, -v174, v112, v1
	v_fma_f32 v215, v174, v114, v215
	v_fma_f32 v114, v173, v114, v1
	v_fma_f32 v112, v173, v112, v215
	v_cvt_pk_bf16_f32 v197, v114, v112
	ds_write_b32 v107, v197 offset:4880
	v_fma_f32 v2, -v174, v112, v2
	v_fma_f32 v216, v174, v114, v216
	v_fma_f32 v114, v173, v114, v2
	v_fma_f32 v112, v173, v112, v216
	v_cvt_pk_bf16_f32 v197, v114, v112
	ds_write_b32 v107, v197 offset:5152
	v_fma_f32 v3, -v174, v112, v3
	v_fma_f32 v217, v174, v114, v217
	v_fma_f32 v114, v173, v114, v3
	v_fma_f32 v112, v173, v112, v217
	v_cvt_pk_bf16_f32 v197, v114, v112
	ds_write_b32 v107, v197 offset:5424
	v_fma_f32 v234, -v174, v112, v234
	v_fma_f32 v198, v174, v114, v198
	v_fma_f32 v114, v173, v114, v234
	v_fma_f32 v112, v173, v112, v198
	v_cvt_pk_bf16_f32 v197, v114, v112
	ds_write_b32 v107, v197 offset:5696
	v_fma_f32 v235, -v174, v112, v235
	v_fma_f32 v199, v174, v114, v199
	v_fma_f32 v114, v173, v114, v235
	v_fma_f32 v112, v173, v112, v199
	v_cvt_pk_bf16_f32 v197, v114, v112
	ds_write_b32 v107, v197 offset:5968
	v_fma_f32 v236, -v174, v112, v236
	v_fma_f32 v200, v174, v114, v200
	v_fma_f32 v114, v173, v114, v236
	v_fma_f32 v112, v173, v112, v200
	v_cvt_pk_bf16_f32 v197, v114, v112
	ds_write_b32 v107, v197 offset:6240
	v_fma_f32 v237, -v174, v112, v237
	v_fma_f32 v201, v174, v114, v201
	v_fma_f32 v114, v173, v114, v237
	v_fma_f32 v112, v173, v112, v201
	v_cvt_pk_bf16_f32 v197, v114, v112
	ds_write_b32 v107, v197 offset:6512
	v_fma_f32 v4, -v174, v112, v4
	v_fma_f32 v218, v174, v114, v218
	v_fma_f32 v114, v173, v114, v4
	v_fma_f32 v112, v173, v112, v218
	v_cvt_pk_bf16_f32 v197, v114, v112
	ds_write_b32 v107, v197 offset:6784
	v_fma_f32 v5, -v174, v112, v5
	v_fma_f32 v219, v174, v114, v219
	v_fma_f32 v114, v173, v114, v5
	v_fma_f32 v112, v173, v112, v219
	v_cvt_pk_bf16_f32 v197, v114, v112
	ds_write_b32 v107, v197 offset:7056
	v_fma_f32 v6, -v174, v112, v6
	v_fma_f32 v220, v174, v114, v220
	v_fma_f32 v114, v173, v114, v6
	v_fma_f32 v112, v173, v112, v220
	v_cvt_pk_bf16_f32 v197, v114, v112
	ds_write_b32 v107, v197 offset:7328
	v_fma_f32 v7, -v174, v112, v7
	v_fma_f32 v221, v174, v114, v221
	v_fma_f32 v114, v173, v114, v7
	v_fma_f32 v112, v173, v112, v221
	v_cvt_pk_bf16_f32 v197, v114, v112
	ds_write_b32 v107, v197 offset:7600
	v_fma_f32 v238, -v174, v112, v238
	v_fma_f32 v202, v174, v114, v202
	v_fma_f32 v114, v173, v114, v238
	v_fma_f32 v112, v173, v112, v202
	v_cvt_pk_bf16_f32 v197, v114, v112
	ds_write_b32 v107, v197 offset:7872
	v_fma_f32 v239, -v174, v112, v239
	v_fma_f32 v203, v174, v114, v203
	v_fma_f32 v114, v173, v114, v239
	v_fma_f32 v112, v173, v112, v203
	v_cvt_pk_bf16_f32 v197, v114, v112
	ds_write_b32 v107, v197 offset:8144
	v_fma_f32 v240, -v174, v112, v240
	v_fma_f32 v204, v174, v114, v204
	v_fma_f32 v114, v173, v114, v240
	v_fma_f32 v112, v173, v112, v204
	v_cvt_pk_bf16_f32 v197, v114, v112
	ds_write_b32 v107, v197 offset:8416
	v_fma_f32 v241, -v174, v112, v241
	v_fma_f32 v205, v174, v114, v205
	v_fma_f32 v114, v173, v114, v241
	v_fma_f32 v112, v173, v112, v205
	v_cvt_pk_bf16_f32 v197, v114, v112
	ds_write_b32 v107, v197 offset:8688
	v_fma_f32 v8, -v174, v112, v8
	v_fma_f32 v222, v174, v114, v222
	v_fma_f32 v114, v173, v114, v8
	v_fma_f32 v112, v173, v112, v222
	v_cvt_pk_bf16_f32 v197, v114, v112
	ds_write_b32 v107, v197 offset:8960
	v_fma_f32 v9, -v174, v112, v9
	v_fma_f32 v223, v174, v114, v223
; __device__ __forceinline__ float bf_lo(unsigned w) { return __uint_as_float(w << 16); }
; __device__ __forceinline__ float bf_hi(unsigned w) { return __uint_as_float(w & 0xffff0000u); }
; #define LAS __attribute__((address_space(3)))
; #define LDS_FENCE() asm volatile("s_waitcnt lgkmcnt(0)" ::: "memory")
; __device__ __forceinline__ unsigned cvt_pk_nv(float lo, float hi) { unsigned r; asm("v_cvt_pk_bf16_f32 %0, %1, %2" : "=v"(r) : "v"(lo), "v"(hi)); return r; }
;     __device__ __forceinline__ float* out() const { return (float*)karg_in(33); }
; template <bool PASS2>
; __device__ __forceinline__ void s5_tile(const Ctx& C, int T, int sb_lo, int sb_hi, LAS unsigned char* lds, int wave, int lane) {
;     ...
;                 for (int t = 0; t < 32; ++t) {
;                     if (sample && t == 0) { xr = s0ar; xi = s0ai; }
;                     if (sample && t == 16) { xr = s0br; xi = s0bi; }
;                     const float nr = fmaf(lr[gi], xr, fmaf(-li[gi], xi, bf_lo(bu[t]))), ni = fmaf(lr[gi], xi, fmaf(li[gi], xr, bf_hi(bu[t])));
;                     xr = nr; xi = ni;
;                     if (PASS2) {
;                         *(LAS unsigned*)(BH + t * BH_STRIDE + 2 * lane) = cvt_pk_nv(xr, xi);
;                         if (sample && (t & 15) == 15) { const int seq = 2 * sb + (t >> 4);
;                             C.out()[OFF_SRE_S + ((size_t)seq * NG + g) * NP + lane] = xr; C.out()[OFF_SIM_S + ((size_t)seq * NG + g) * NP + lane] = xi; }
;                     }
;                 }
;                 sr[gi] = xr; si[gi] = xi;
;             }
;             LDS_FENCE();
;             if (PASS2) {
; #pragma unroll
;                 for (int rb = 0; rb < 2; ++rb) {
;                     v4f acc = (v4f){0.f, 0.f, 0.f, 0.f};
; #pragma unroll
;                     for (int ks = 0; ks < 4; ++ks) {
;                         const bfx8 sa = *(const LAS bfx8*)(BH + (16 * rb + fr) * BH_STRIDE + 32 * ks + 8 * kq);
;                         acc = __builtin_amdgcn_mfma_f32_16x16x32_bf16(sa, cm[ks], acc, 0, 0, 0);
;                     }
; #pragma unroll
;                     for (int r = 0; r < 4; ++r) {
;                         LAS bf16* up = XU + (16 * rb + 4 * kq + r) * XU_STRIDE + 16 * gi + fr;
;                         const float u = __uint_as_float((unsigned)(*up) << 16);
	v_fma_f32 v114, v173, v114, v9
	v_fma_f32 v112, v173, v112, v223
	v_cvt_pk_bf16_f32 v197, v114, v112
	ds_write_b32 v107, v197 offset:9232
	v_fma_f32 v10, -v174, v112, v10
	v_fma_f32 v224, v174, v114, v224
	v_fma_f32 v114, v173, v114, v10
	v_fma_f32 v112, v173, v112, v224
	v_cvt_pk_bf16_f32 v197, v114, v112
	ds_write_b32 v107, v197 offset:9504
	v_fma_f32 v11, -v174, v112, v11
	v_fma_f32 v225, v174, v114, v225
	v_fma_f32 v114, v173, v114, v11
	v_fma_f32 v112, v173, v112, v225
	v_cvt_pk_bf16_f32 v197, v114, v112
	ds_write_b32 v107, v197 offset:9776
	v_fma_f32 v242, -v174, v112, v242
	v_fma_f32 v206, v174, v114, v206
	v_fma_f32 v114, v173, v114, v242
	v_fma_f32 v112, v173, v112, v206
	v_cvt_pk_bf16_f32 v197, v114, v112
	ds_write_b32 v107, v197 offset:10048
	v_fma_f32 v243, -v174, v112, v243
	v_fma_f32 v207, v174, v114, v207
	v_fma_f32 v114, v173, v114, v243
	v_fma_f32 v112, v173, v112, v207
	v_cvt_pk_bf16_f32 v197, v114, v112
	ds_write_b32 v107, v197 offset:10320
	v_fma_f32 v244, -v174, v112, v244
	v_fma_f32 v208, v174, v114, v208
	v_fma_f32 v114, v173, v114, v244
	v_fma_f32 v112, v173, v112, v208
	v_cvt_pk_bf16_f32 v197, v114, v112
	ds_write_b32 v107, v197 offset:10592
	v_fma_f32 v245, -v174, v112, v245
	v_fma_f32 v209, v174, v114, v209
	v_fma_f32 v114, v173, v114, v245
	v_fma_f32 v112, v173, v112, v209
	v_cvt_pk_bf16_f32 v197, v114, v112
	ds_write_b32 v107, v197 offset:10864
	v_fma_f32 v12, -v174, v112, v12
	v_fma_f32 v226, v174, v114, v226
	v_fma_f32 v114, v173, v114, v12
	v_fma_f32 v112, v173, v112, v226
	v_cvt_pk_bf16_f32 v197, v114, v112
	ds_write_b32 v107, v197 offset:11136
	v_fma_f32 v13, -v174, v112, v13
	v_fma_f32 v227, v174, v114, v227
	v_fma_f32 v114, v173, v114, v13
	v_fma_f32 v112, v173, v112, v227
	v_cvt_pk_bf16_f32 v197, v114, v112
	ds_write_b32 v107, v197 offset:11408
	v_fma_f32 v14, -v174, v112, v14
	v_fma_f32 v228, v174, v114, v228
	v_fma_f32 v114, v173, v114, v14
	v_fma_f32 v112, v173, v112, v228
	v_cvt_pk_bf16_f32 v197, v114, v112
	ds_write_b32 v107, v197 offset:11680
	v_fma_f32 v15, -v174, v112, v15
	v_fma_f32 v229, v174, v114, v229
	v_fma_f32 v114, v173, v114, v15
	v_fma_f32 v112, v173, v112, v229
	v_cvt_pk_bf16_f32 v197, v114, v112
	ds_write_b32 v107, v197 offset:11952
	v_fma_f32 v246, -v174, v112, v246
	v_fma_f32 v210, v174, v114, v210
	v_fma_f32 v114, v173, v114, v246
	v_fma_f32 v112, v173, v112, v210
	v_cvt_pk_bf16_f32 v197, v114, v112
	ds_write_b32 v107, v197 offset:12224
	v_fma_f32 v247, -v174, v112, v247
	v_fma_f32 v211, v174, v114, v211
	v_fma_f32 v114, v173, v114, v247
	v_fma_f32 v112, v173, v112, v211
	v_cvt_pk_bf16_f32 v197, v114, v112
	ds_write_b32 v107, v197 offset:12496
	v_fma_f32 v248, -v174, v112, v248
	v_fma_f32 v212, v174, v114, v212
	v_fma_f32 v114, v173, v114, v248
	v_fma_f32 v112, v173, v112, v212
	v_cvt_pk_bf16_f32 v197, v114, v112
	ds_write_b32 v107, v197 offset:12768
	v_fma_f32 v249, -v174, v112, v249
	v_fma_f32 v213, v174, v114, v213
	v_fma_f32 v114, v173, v114, v249
	v_fma_f32 v112, v173, v112, v213
	v_cvt_pk_bf16_f32 v197, v114, v112
	ds_write_b32 v107, v197 offset:13040
	s_waitcnt lgkmcnt(0)
	ds_read_b128 v[214:217], v194 offset:4608
	ds_read_b128 v[218:221], v194 offset:4672
	ds_read_b128 v[222:225], v194 offset:4736
	ds_read_b128 v[226:229], v194 offset:4800
	ds_read_b128 v[234:237], v194 offset:8960
	ds_read_b128 v[238:241], v194 offset:9024
	ds_read_b128 v[242:245], v194 offset:9088
	ds_read_b128 v[246:249], v194 offset:9152
	ds_read_u16 v8, v195
	ds_read_u16 v9, v195 offset:144
	ds_read_u16 v10, v195 offset:288
	ds_read_u16 v11, v195 offset:432
	ds_read_u16 v12, v195 offset:2304
	ds_read_u16 v13, v195 offset:2448
	ds_read_u16 v14, v195 offset:2592
	ds_read_u16 v15, v195 offset:2736
	s_waitcnt lgkmcnt(8)
	v_mfma_f32_16x16x32_bf16 v[0:3], v[214:217], v[44:47], 0
	v_mfma_f32_16x16x32_bf16 v[4:7], v[234:237], v[44:47], 0
	v_mfma_f32_16x16x32_bf16 v[0:3], v[218:221], v[40:43], v[0:3]
	v_mfma_f32_16x16x32_bf16 v[4:7], v[238:241], v[40:43], v[4:7]
	v_mfma_f32_16x16x32_bf16 v[0:3], v[222:225], v[36:39], v[0:3]
	v_mfma_f32_16x16x32_bf16 v[4:7], v[242:245], v[36:39], v[4:7]
	v_mfma_f32_16x16x32_bf16 v[0:3], v[226:229], v[32:35], v[0:3]
	v_mfma_f32_16x16x32_bf16 v[4:7], v[246:249], v[32:35], v[4:7]
	s_waitcnt lgkmcnt(0)
; __device__ __forceinline__ float gelu_t(float x) { const float u = 1.5957691216057308f * (x + 0.044715f * x * x * x); return x * sigmoid_f(u); }
; #define LAS __attribute__((address_space(3)))
; template <bool PASS2>
; __device__ __forceinline__ void s5_tile(const Ctx& C, int T, int sb_lo, int sb_hi, LAS unsigned char* lds, int wave, int lane) {
;     ...
;         for (int gi = 0; gi < 4; ++gi) {
;             const int g = wave * 4 + gi, gnx = wave * 4 + ((gi + 1) & 3);
;             bfx8 bb[4], cm[4];
; #pragma unroll
;             for (int cb = 0; cb < 4; ++cb) { bb[cb] = bbn[cb]; bbn[cb] = *(const bfx8*)(BBt + ((size_t)(gnx * 128 + cb * 32 + tl)) * GN + 8 * hh); }
;             if (PASS2) {
; #pragma unroll
;                 for (int ks = 0; ks < 4; ++ks) { cm[ks] = cmn[ks]; cmn[ks] = *(const bfx8*)(CMt + ((size_t)(gnx * GN + fr)) * 128 + 32 * ks + 8 * kq); }
;             }
;             float s0ar = 0.f, s0ai = 0.f, s0br = 0.f, s0bi = 0.f;
;             if (sample) { const size_t o0 = ((size_t)(2 * sb) * NG + g) * NP + lane, o1 = o0 + (size_t)NG * NP;
;                 s0ar = C.in(2)[o0]; s0ai = C.in(3)[o0]; s0br = C.in(2)[o1]; s0bi = C.in(3)[o1]; }
;             const bfx8 a = *(const LAS bfx8*)(XU + tl * XU_STRIDE + 16 * gi + 8 * hh);
; #pragma unroll
;             for (int cb = 0; cb < 4; ++cb) {
;                 v16f acc;
; #pragma unroll
;                 for (int r = 0; r < 16; ++r) acc[r] = 0.f;
;                 acc = __builtin_amdgcn_mfma_f32_32x32x16_bf16(bb[cb], a, acc, 0, 0, 0);
;     ...
;             if (PASS2) {
; #pragma unroll
;                 for (int rb = 0; rb < 2; ++rb) {
;                     v4f acc = (v4f){0.f, 0.f, 0.f, 0.f};
; #pragma unroll
;                     for (int ks = 0; ks < 4; ++ks) {
;                         const bfx8 sa = *(const LAS bfx8*)(BH + (16 * rb + fr) * BH_STRIDE + 32 * ks + 8 * kq);
;                         acc = __builtin_amdgcn_mfma_f32_16x16x32_bf16(sa, cm[ks], acc, 0, 0, 0);
;                     }
; #pragma unroll
;                     for (int r = 0; r < 4; ++r) {
;                         LAS bf16* up = XU + (16 * rb + 4 * kq + r) * XU_STRIDE + 16 * gi + fr;
;                         const float u = __uint_as_float((unsigned)(*up) << 16);
;                         *up = f2bf(gelu_t(acc[r] + dsk[gi] * u));
;                     }
	v_lshlrev_b32_e32 v8, 16, v8
	v_lshlrev_b32_e32 v9, 16, v9
	v_lshlrev_b32_e32 v10, 16, v10
	v_lshlrev_b32_e32 v11, 16, v11
	v_lshlrev_b32_e32 v12, 16, v12
	v_lshlrev_b32_e32 v13, 16, v13
	v_lshlrev_b32_e32 v14, 16, v14
	v_lshlrev_b32_e32 v15, 16, v15
	v_fma_f32 v0, v175, v8, v0
	v_fma_f32 v1, v175, v9, v1
	v_fma_f32 v2, v175, v10, v2
	v_fma_f32 v3, v175, v11, v3
	v_fma_f32 v4, v175, v12, v4
	v_fma_f32 v5, v175, v13, v5
	v_fma_f32 v6, v175, v14, v6
	v_fma_f32 v7, v175, v15, v7
	v_mul_f32_e32 v198, 0x3d372713, v0
	v_mul_f32_e32 v199, 0x3d372713, v1
	v_mul_f32_e32 v200, 0x3d372713, v2
	v_mul_f32_e32 v201, 0x3d372713, v3
	v_mul_f32_e32 v202, 0x3d372713, v4
	v_mul_f32_e32 v203, 0x3d372713, v5
	v_mul_f32_e32 v204, 0x3d372713, v6
	v_mul_f32_e32 v205, 0x3d372713, v7
	v_mul_f32_e32 v198, v0, v198
	v_mul_f32_e32 v199, v1, v199
	v_mul_f32_e32 v200, v2, v200
	v_mul_f32_e32 v201, v3, v201
	v_mul_f32_e32 v202, v4, v202
	v_mul_f32_e32 v203, v5, v203
	v_mul_f32_e32 v204, v6, v204
	v_mul_f32_e32 v205, v7, v205
	v_fma_f32 v198, v0, v198, v0
	v_fma_f32 v199, v1, v199, v1
	v_fma_f32 v200, v2, v200, v2
	v_fma_f32 v201, v3, v201, v3
	v_fma_f32 v202, v4, v202, v4
	v_fma_f32 v203, v5, v203, v5
	v_fma_f32 v204, v6, v204, v6
	v_fma_f32 v205, v7, v205, v7
	v_mul_f32_e32 v198, 0x3fcc422a, v198
	v_mul_f32_e32 v199, 0x3fcc422a, v199
	v_mul_f32_e32 v200, 0x3fcc422a, v200
	v_mul_f32_e32 v201, 0x3fcc422a, v201
	v_mul_f32_e32 v202, 0x3fcc422a, v202
	v_mul_f32_e32 v203, 0x3fcc422a, v203
	v_mul_f32_e32 v204, 0x3fcc422a, v204
	v_mul_f32_e32 v205, 0x3fcc422a, v205
	v_mul_f32_e32 v198, 0xbfb8aa3b, v198
	v_mul_f32_e32 v199, 0xbfb8aa3b, v199
	v_mul_f32_e32 v200, 0xbfb8aa3b, v200
	v_mul_f32_e32 v201, 0xbfb8aa3b, v201
	v_mul_f32_e32 v202, 0xbfb8aa3b, v202
	v_mul_f32_e32 v203, 0xbfb8aa3b, v203
	v_mul_f32_e32 v204, 0xbfb8aa3b, v204
	v_mul_f32_e32 v205, 0xbfb8aa3b, v205
	v_exp_f32_e32 v198, v198
	v_exp_f32_e32 v199, v199
	v_exp_f32_e32 v200, v200
	v_exp_f32_e32 v201, v201
	v_exp_f32_e32 v202, v202
	v_exp_f32_e32 v203, v203
	v_exp_f32_e32 v204, v204
	v_exp_f32_e32 v205, v205
	v_add_f32_e32 v198, 1.0, v198
	v_add_f32_e32 v199, 1.0, v199
	v_add_f32_e32 v200, 1.0, v200
	v_add_f32_e32 v201, 1.0, v201
	v_add_f32_e32 v202, 1.0, v202
	v_add_f32_e32 v203, 1.0, v203
	v_add_f32_e32 v204, 1.0, v204
	v_add_f32_e32 v205, 1.0, v205
	v_rcp_f32_e32 v198, v198
	v_rcp_f32_e32 v199, v199
	v_rcp_f32_e32 v200, v200
	v_rcp_f32_e32 v201, v201
	v_rcp_f32_e32 v202, v202
	v_rcp_f32_e32 v203, v203
	v_rcp_f32_e32 v204, v204
	v_rcp_f32_e32 v205, v205
	v_mul_f32_e32 v0, v0, v198
	v_mul_f32_e32 v1, v1, v199
	v_mul_f32_e32 v2, v2, v200
	v_mul_f32_e32 v3, v3, v201
	v_mul_f32_e32 v4, v4, v202
	v_mul_f32_e32 v5, v5, v203
	v_mul_f32_e32 v6, v6, v204
	v_mul_f32_e32 v7, v7, v205
	v_cvt_pk_bf16_f32 v0, v0, v101
	v_cvt_pk_bf16_f32 v1, v1, v101
	v_cvt_pk_bf16_f32 v2, v2, v101
	v_cvt_pk_bf16_f32 v3, v3, v101
	v_cvt_pk_bf16_f32 v4, v4, v101
	v_cvt_pk_bf16_f32 v5, v5, v101
	v_cvt_pk_bf16_f32 v6, v6, v101
	v_cvt_pk_bf16_f32 v7, v7, v101
	ds_write_b16 v195, v0
	ds_write_b16 v195, v1 offset:144
	ds_write_b16 v195, v2 offset:288
	ds_write_b16 v195, v3 offset:432
	ds_write_b16 v195, v4 offset:2304
	ds_write_b16 v195, v5 offset:2448
	ds_write_b16 v195, v6 offset:2592
	ds_write_b16 v195, v7 offset:2736
	s_waitcnt lgkmcnt(0)
	global_load_dwordx4 v[76:79], v[136:137], off
	global_load_dwordx4 v[72:75], v[138:139], off
	global_load_dwordx4 v[68:71], v[140:141], off
	global_load_dwordx4 v[64:67], v[142:143], off
	ds_read_b128 v[250:253], v192 offset:32
	s_waitcnt vmcnt(11) lgkmcnt(0)
	v_mfma_f32_32x32x16_bf16 v[0:15], v[250:253], v[92:95], 0
	global_load_dwordx4 v[44:47], v[144:145], off
	global_load_dwordx4 v[40:43], v[144:145], off offset:1024
	global_load_dwordx4 v[32:35], v[144:145], off offset:2048
	global_load_dwordx4 v[36:39], v[144:145], off offset:3072
	s_waitcnt vmcnt(14)
	v_mfma_f32_32x32x16_bf16 v[214:229], v[250:253], v[88:91], 0
	s_waitcnt vmcnt(13)
	v_mfma_f32_32x32x16_bf16 v[234:249], v[250:253], v[84:87], 0
	s_waitcnt vmcnt(12)
	v_mfma_f32_32x32x16_bf16 v[198:213], v[250:253], v[80:83], 0
	s_nop 11
	v_permlane32_swap_b32_e32 v0, v234
	v_permlane32_swap_b32_e32 v1, v235
	v_permlane32_swap_b32_e32 v2, v236
	v_permlane32_swap_b32_e32 v3, v237
	v_permlane32_swap_b32_e32 v4, v238
	v_permlane32_swap_b32_e32 v5, v239
	v_permlane32_swap_b32_e32 v6, v240
	v_permlane32_swap_b32_e32 v7, v241
	v_permlane32_swap_b32_e32 v8, v242
	v_permlane32_swap_b32_e32 v9, v243
	v_permlane32_swap_b32_e32 v10, v244
	v_permlane32_swap_b32_e32 v11, v245
	v_permlane32_swap_b32_e32 v12, v246
	v_permlane32_swap_b32_e32 v13, v247
	v_permlane32_swap_b32_e32 v14, v248
	v_permlane32_swap_b32_e32 v15, v249
	v_permlane32_swap_b32_e32 v214, v198
	v_permlane32_swap_b32_e32 v215, v199
	v_permlane32_swap_b32_e32 v216, v200
	v_permlane32_swap_b32_e32 v217, v201
	v_permlane32_swap_b32_e32 v218, v202
	v_permlane32_swap_b32_e32 v219, v203
	v_permlane32_swap_b32_e32 v220, v204
	v_permlane32_swap_b32_e32 v221, v205
	v_permlane32_swap_b32_e32 v222, v206
	v_permlane32_swap_b32_e32 v223, v207
	v_permlane32_swap_b32_e32 v224, v208
	v_permlane32_swap_b32_e32 v225, v209
	v_permlane32_swap_b32_e32 v226, v210
	v_permlane32_swap_b32_e32 v227, v211
	v_permlane32_swap_b32_e32 v228, v212
	v_permlane32_swap_b32_e32 v229, v213
	v_fma_f32 v0, -v177, v113, v0
	v_fma_f32 v214, v177, v115, v214
	v_fma_f32 v115, v176, v115, v0
	v_fma_f32 v113, v176, v113, v214
	v_cvt_pk_bf16_f32 v197, v115, v113
	ds_write_b32 v107, v197 offset:4608
	v_fma_f32 v1, -v177, v113, v1
	v_fma_f32 v215, v177, v115, v215
	v_fma_f32 v115, v176, v115, v1
	v_fma_f32 v113, v176, v113, v215
	v_cvt_pk_bf16_f32 v197, v115, v113
; __device__ __forceinline__ float bf_lo(unsigned w) { return __uint_as_float(w << 16); }
; __device__ __forceinline__ float bf_hi(unsigned w) { return __uint_as_float(w & 0xffff0000u); }
; #define LAS __attribute__((address_space(3)))
; __device__ __forceinline__ unsigned cvt_pk_nv(float lo, float hi) { unsigned r; asm("v_cvt_pk_bf16_f32 %0, %1, %2" : "=v"(r) : "v"(lo), "v"(hi)); return r; }
; template <bool PASS2>
; __device__ __forceinline__ void s5_tile(const Ctx& C, int T, int sb_lo, int sb_hi, LAS unsigned char* lds, int wave, int lane) {
;     ...
;                 for (int t = 0; t < 32; ++t) {
;                     if (sample && t == 0) { xr = s0ar; xi = s0ai; }
;                     if (sample && t == 16) { xr = s0br; xi = s0bi; }
;                     const float nr = fmaf(lr[gi], xr, fmaf(-li[gi], xi, bf_lo(bu[t]))), ni = fmaf(lr[gi], xi, fmaf(li[gi], xr, bf_hi(bu[t])));
;                     xr = nr; xi = ni;
;                     if (PASS2) {
;                         *(LAS unsigned*)(BH + t * BH_STRIDE + 2 * lane) = cvt_pk_nv(xr, xi);
	ds_write_b32 v107, v197 offset:4880
	v_fma_f32 v2, -v177, v113, v2
	v_fma_f32 v216, v177, v115, v216
	v_fma_f32 v115, v176, v115, v2
	v_fma_f32 v113, v176, v113, v216
	v_cvt_pk_bf16_f32 v197, v115, v113
	ds_write_b32 v107, v197 offset:5152
	v_fma_f32 v3, -v177, v113, v3
	v_fma_f32 v217, v177, v115, v217
	v_fma_f32 v115, v176, v115, v3
	v_fma_f32 v113, v176, v113, v217
	v_cvt_pk_bf16_f32 v197, v115, v113
	ds_write_b32 v107, v197 offset:5424
	v_fma_f32 v234, -v177, v113, v234
	v_fma_f32 v198, v177, v115, v198
	v_fma_f32 v115, v176, v115, v234
	v_fma_f32 v113, v176, v113, v198
	v_cvt_pk_bf16_f32 v197, v115, v113
	ds_write_b32 v107, v197 offset:5696
	v_fma_f32 v235, -v177, v113, v235
	v_fma_f32 v199, v177, v115, v199
	v_fma_f32 v115, v176, v115, v235
	v_fma_f32 v113, v176, v113, v199
	v_cvt_pk_bf16_f32 v197, v115, v113
	ds_write_b32 v107, v197 offset:5968
	v_fma_f32 v236, -v177, v113, v236
	v_fma_f32 v200, v177, v115, v200
	v_fma_f32 v115, v176, v115, v236
	v_fma_f32 v113, v176, v113, v200
	v_cvt_pk_bf16_f32 v197, v115, v113
	ds_write_b32 v107, v197 offset:6240
	v_fma_f32 v237, -v177, v113, v237
	v_fma_f32 v201, v177, v115, v201
	v_fma_f32 v115, v176, v115, v237
	v_fma_f32 v113, v176, v113, v201
	v_cvt_pk_bf16_f32 v197, v115, v113
	ds_write_b32 v107, v197 offset:6512
	v_fma_f32 v4, -v177, v113, v4
	v_fma_f32 v218, v177, v115, v218
	v_fma_f32 v115, v176, v115, v4
	v_fma_f32 v113, v176, v113, v218
	v_cvt_pk_bf16_f32 v197, v115, v113
	ds_write_b32 v107, v197 offset:6784
	v_fma_f32 v5, -v177, v113, v5
	v_fma_f32 v219, v177, v115, v219
	v_fma_f32 v115, v176, v115, v5
	v_fma_f32 v113, v176, v113, v219
	v_cvt_pk_bf16_f32 v197, v115, v113
	ds_write_b32 v107, v197 offset:7056
	v_fma_f32 v6, -v177, v113, v6
	v_fma_f32 v220, v177, v115, v220
	v_fma_f32 v115, v176, v115, v6
	v_fma_f32 v113, v176, v113, v220
	v_cvt_pk_bf16_f32 v197, v115, v113
	ds_write_b32 v107, v197 offset:7328
	v_fma_f32 v7, -v177, v113, v7
	v_fma_f32 v221, v177, v115, v221
	v_fma_f32 v115, v176, v115, v7
	v_fma_f32 v113, v176, v113, v221
	v_cvt_pk_bf16_f32 v197, v115, v113
	ds_write_b32 v107, v197 offset:7600
	v_fma_f32 v238, -v177, v113, v238
	v_fma_f32 v202, v177, v115, v202
	v_fma_f32 v115, v176, v115, v238
	v_fma_f32 v113, v176, v113, v202
	v_cvt_pk_bf16_f32 v197, v115, v113
	ds_write_b32 v107, v197 offset:7872
	v_fma_f32 v239, -v177, v113, v239
	v_fma_f32 v203, v177, v115, v203
	v_fma_f32 v115, v176, v115, v239
	v_fma_f32 v113, v176, v113, v203
	v_cvt_pk_bf16_f32 v197, v115, v113
	ds_write_b32 v107, v197 offset:8144
	v_fma_f32 v240, -v177, v113, v240
	v_fma_f32 v204, v177, v115, v204
	v_fma_f32 v115, v176, v115, v240
	v_fma_f32 v113, v176, v113, v204
	v_cvt_pk_bf16_f32 v197, v115, v113
	ds_write_b32 v107, v197 offset:8416
	v_fma_f32 v241, -v177, v113, v241
	v_fma_f32 v205, v177, v115, v205
	v_fma_f32 v115, v176, v115, v241
	v_fma_f32 v113, v176, v113, v205
	v_cvt_pk_bf16_f32 v197, v115, v113
	ds_write_b32 v107, v197 offset:8688
	v_fma_f32 v8, -v177, v113, v8
	v_fma_f32 v222, v177, v115, v222
	v_fma_f32 v115, v176, v115, v8
	v_fma_f32 v113, v176, v113, v222
	v_cvt_pk_bf16_f32 v197, v115, v113
	ds_write_b32 v107, v197 offset:8960
	v_fma_f32 v9, -v177, v113, v9
	v_fma_f32 v223, v177, v115, v223
	v_fma_f32 v115, v176, v115, v9
	v_fma_f32 v113, v176, v113, v223
	v_cvt_pk_bf16_f32 v197, v115, v113
	ds_write_b32 v107, v197 offset:9232
	v_fma_f32 v10, -v177, v113, v10
	v_fma_f32 v224, v177, v115, v224
	v_fma_f32 v115, v176, v115, v10
	v_fma_f32 v113, v176, v113, v224
	v_cvt_pk_bf16_f32 v197, v115, v113
	ds_write_b32 v107, v197 offset:9504
	v_fma_f32 v11, -v177, v113, v11
	v_fma_f32 v225, v177, v115, v225
	v_fma_f32 v115, v176, v115, v11
	v_fma_f32 v113, v176, v113, v225
	v_cvt_pk_bf16_f32 v197, v115, v113
	ds_write_b32 v107, v197 offset:9776
	v_fma_f32 v242, -v177, v113, v242
	v_fma_f32 v206, v177, v115, v206
	v_fma_f32 v115, v176, v115, v242
	v_fma_f32 v113, v176, v113, v206
	v_cvt_pk_bf16_f32 v197, v115, v113
	ds_write_b32 v107, v197 offset:10048
	v_fma_f32 v243, -v177, v113, v243
	v_fma_f32 v207, v177, v115, v207
	v_fma_f32 v115, v176, v115, v243
	v_fma_f32 v113, v176, v113, v207
	v_cvt_pk_bf16_f32 v197, v115, v113
	ds_write_b32 v107, v197 offset:10320
	v_fma_f32 v244, -v177, v113, v244
	v_fma_f32 v208, v177, v115, v208
	v_fma_f32 v115, v176, v115, v244
	v_fma_f32 v113, v176, v113, v208
	v_cvt_pk_bf16_f32 v197, v115, v113
	ds_write_b32 v107, v197 offset:10592
	v_fma_f32 v245, -v177, v113, v245
	v_fma_f32 v209, v177, v115, v209
	v_fma_f32 v115, v176, v115, v245
	v_fma_f32 v113, v176, v113, v209
	v_cvt_pk_bf16_f32 v197, v115, v113
	ds_write_b32 v107, v197 offset:10864
	v_fma_f32 v12, -v177, v113, v12
	v_fma_f32 v226, v177, v115, v226
	v_fma_f32 v115, v176, v115, v12
	v_fma_f32 v113, v176, v113, v226
	v_cvt_pk_bf16_f32 v197, v115, v113
	ds_write_b32 v107, v197 offset:11136
	v_fma_f32 v13, -v177, v113, v13
	v_fma_f32 v227, v177, v115, v227
	v_fma_f32 v115, v176, v115, v13
	v_fma_f32 v113, v176, v113, v227
	v_cvt_pk_bf16_f32 v197, v115, v113
	ds_write_b32 v107, v197 offset:11408
	v_fma_f32 v14, -v177, v113, v14
	v_fma_f32 v228, v177, v115, v228
	v_fma_f32 v115, v176, v115, v14
	v_fma_f32 v113, v176, v113, v228
	v_cvt_pk_bf16_f32 v197, v115, v113
	ds_write_b32 v107, v197 offset:11680
	v_fma_f32 v15, -v177, v113, v15
	v_fma_f32 v229, v177, v115, v229
	v_fma_f32 v115, v176, v115, v15
	v_fma_f32 v113, v176, v113, v229
	v_cvt_pk_bf16_f32 v197, v115, v113
	ds_write_b32 v107, v197 offset:11952
	v_fma_f32 v246, -v177, v113, v246
	v_fma_f32 v210, v177, v115, v210
	v_fma_f32 v115, v176, v115, v246
	v_fma_f32 v113, v176, v113, v210
	v_cvt_pk_bf16_f32 v197, v115, v113
	ds_write_b32 v107, v197 offset:12224
	v_fma_f32 v247, -v177, v113, v247
	v_fma_f32 v211, v177, v115, v211
	v_fma_f32 v115, v176, v115, v247
	v_fma_f32 v113, v176, v113, v211
	v_cvt_pk_bf16_f32 v197, v115, v113
	ds_write_b32 v107, v197 offset:12496
	v_fma_f32 v248, -v177, v113, v248
	v_fma_f32 v212, v177, v115, v212
	v_fma_f32 v115, v176, v115, v248
	v_fma_f32 v113, v176, v113, v212
	v_cvt_pk_bf16_f32 v197, v115, v113
	ds_write_b32 v107, v197 offset:12768
	v_fma_f32 v249, -v177, v113, v249
	v_fma_f32 v213, v177, v115, v213
	v_fma_f32 v115, v176, v115, v249
	v_fma_f32 v113, v176, v113, v213
	v_cvt_pk_bf16_f32 v197, v115, v113
	ds_write_b32 v107, v197 offset:13040
	s_waitcnt lgkmcnt(0)
; __device__ __forceinline__ float gelu_t(float x) { const float u = 1.5957691216057308f * (x + 0.044715f * x * x * x); return x * sigmoid_f(u); }
; #define LAS __attribute__((address_space(3)))
; template <bool PASS2>
; __device__ __forceinline__ void s5_tile(const Ctx& C, int T, int sb_lo, int sb_hi, LAS unsigned char* lds, int wave, int lane) {
;     ...
;         for (int gi = 0; gi < 4; ++gi) {
;             const int g = wave * 4 + gi, gnx = wave * 4 + ((gi + 1) & 3);
;             bfx8 bb[4], cm[4];
; #pragma unroll
;             for (int cb = 0; cb < 4; ++cb) { bb[cb] = bbn[cb]; bbn[cb] = *(const bfx8*)(BBt + ((size_t)(gnx * 128 + cb * 32 + tl)) * GN + 8 * hh); }
;             if (PASS2) {
; #pragma unroll
;                 for (int ks = 0; ks < 4; ++ks) { cm[ks] = cmn[ks]; cmn[ks] = *(const bfx8*)(CMt + ((size_t)(gnx * GN + fr)) * 128 + 32 * ks + 8 * kq); }
;             }
;             float s0ar = 0.f, s0ai = 0.f, s0br = 0.f, s0bi = 0.f;
;             if (sample) { const size_t o0 = ((size_t)(2 * sb) * NG + g) * NP + lane, o1 = o0 + (size_t)NG * NP;
;                 s0ar = C.in(2)[o0]; s0ai = C.in(3)[o0]; s0br = C.in(2)[o1]; s0bi = C.in(3)[o1]; }
;             const bfx8 a = *(const LAS bfx8*)(XU + tl * XU_STRIDE + 16 * gi + 8 * hh);
; #pragma unroll
;             for (int cb = 0; cb < 4; ++cb) {
;                 v16f acc;
; #pragma unroll
;                 for (int r = 0; r < 16; ++r) acc[r] = 0.f;
;                 acc = __builtin_amdgcn_mfma_f32_32x32x16_bf16(bb[cb], a, acc, 0, 0, 0);
;     ...
;             if (PASS2) {
; #pragma unroll
;                 for (int rb = 0; rb < 2; ++rb) {
;                     v4f acc = (v4f){0.f, 0.f, 0.f, 0.f};
; #pragma unroll
;                     for (int ks = 0; ks < 4; ++ks) {
;                         const bfx8 sa = *(const LAS bfx8*)(BH + (16 * rb + fr) * BH_STRIDE + 32 * ks + 8 * kq);
;                         acc = __builtin_amdgcn_mfma_f32_16x16x32_bf16(sa, cm[ks], acc, 0, 0, 0);
;                     }
; #pragma unroll
;                     for (int r = 0; r < 4; ++r) {
;                         LAS bf16* up = XU + (16 * rb + 4 * kq + r) * XU_STRIDE + 16 * gi + fr;
;                         const float u = __uint_as_float((unsigned)(*up) << 16);
;                         *up = f2bf(gelu_t(acc[r] + dsk[gi] * u));
;                     }
	ds_read_b128 v[214:217], v194 offset:4608
	ds_read_b128 v[218:221], v194 offset:4672
	ds_read_b128 v[222:225], v194 offset:4736
	ds_read_b128 v[226:229], v194 offset:4800
	ds_read_b128 v[234:237], v194 offset:8960
	ds_read_b128 v[238:241], v194 offset:9024
	ds_read_b128 v[242:245], v194 offset:9088
	ds_read_b128 v[246:249], v194 offset:9152
	ds_read_u16 v8, v195 offset:32
	ds_read_u16 v9, v195 offset:176
	ds_read_u16 v10, v195 offset:320
	ds_read_u16 v11, v195 offset:464
	ds_read_u16 v12, v195 offset:2336
	ds_read_u16 v13, v195 offset:2480
	ds_read_u16 v14, v195 offset:2624
	ds_read_u16 v15, v195 offset:2768
	s_waitcnt vmcnt(8) lgkmcnt(8)
	v_mfma_f32_16x16x32_bf16 v[0:3], v[214:217], v[60:63], 0
	v_mfma_f32_16x16x32_bf16 v[4:7], v[234:237], v[60:63], 0
	v_mfma_f32_16x16x32_bf16 v[0:3], v[218:221], v[56:59], v[0:3]
	v_mfma_f32_16x16x32_bf16 v[4:7], v[238:241], v[56:59], v[4:7]
	v_mfma_f32_16x16x32_bf16 v[0:3], v[222:225], v[48:51], v[0:3]
	v_mfma_f32_16x16x32_bf16 v[4:7], v[242:245], v[48:51], v[4:7]
	v_mfma_f32_16x16x32_bf16 v[0:3], v[226:229], v[52:55], v[0:3]
	v_mfma_f32_16x16x32_bf16 v[4:7], v[246:249], v[52:55], v[4:7]
	s_waitcnt lgkmcnt(0)
	v_lshlrev_b32_e32 v8, 16, v8
	v_lshlrev_b32_e32 v9, 16, v9
	v_lshlrev_b32_e32 v10, 16, v10
	v_lshlrev_b32_e32 v11, 16, v11
	v_lshlrev_b32_e32 v12, 16, v12
	v_lshlrev_b32_e32 v13, 16, v13
	v_lshlrev_b32_e32 v14, 16, v14
	v_lshlrev_b32_e32 v15, 16, v15
	v_fma_f32 v0, v178, v8, v0
	v_fma_f32 v1, v178, v9, v1
	v_fma_f32 v2, v178, v10, v2
	v_fma_f32 v3, v178, v11, v3
	v_fma_f32 v4, v178, v12, v4
	v_fma_f32 v5, v178, v13, v5
	v_fma_f32 v6, v178, v14, v6
	v_fma_f32 v7, v178, v15, v7
	v_mul_f32_e32 v198, 0x3d372713, v0
	v_mul_f32_e32 v199, 0x3d372713, v1
	v_mul_f32_e32 v200, 0x3d372713, v2
	v_mul_f32_e32 v201, 0x3d372713, v3
	v_mul_f32_e32 v202, 0x3d372713, v4
	v_mul_f32_e32 v203, 0x3d372713, v5
	v_mul_f32_e32 v204, 0x3d372713, v6
	v_mul_f32_e32 v205, 0x3d372713, v7
	v_mul_f32_e32 v198, v0, v198
	v_mul_f32_e32 v199, v1, v199
	v_mul_f32_e32 v200, v2, v200
	v_mul_f32_e32 v201, v3, v201
	v_mul_f32_e32 v202, v4, v202
	v_mul_f32_e32 v203, v5, v203
	v_mul_f32_e32 v204, v6, v204
	v_mul_f32_e32 v205, v7, v205
	v_fma_f32 v198, v0, v198, v0
	v_fma_f32 v199, v1, v199, v1
	v_fma_f32 v200, v2, v200, v2
	v_fma_f32 v201, v3, v201, v3
	v_fma_f32 v202, v4, v202, v4
	v_fma_f32 v203, v5, v203, v5
	v_fma_f32 v204, v6, v204, v6
	v_fma_f32 v205, v7, v205, v7
	v_mul_f32_e32 v198, 0x3fcc422a, v198
	v_mul_f32_e32 v199, 0x3fcc422a, v199
	v_mul_f32_e32 v200, 0x3fcc422a, v200
	v_mul_f32_e32 v201, 0x3fcc422a, v201
	v_mul_f32_e32 v202, 0x3fcc422a, v202
	v_mul_f32_e32 v203, 0x3fcc422a, v203
	v_mul_f32_e32 v204, 0x3fcc422a, v204
	v_mul_f32_e32 v205, 0x3fcc422a, v205
	v_mul_f32_e32 v198, 0xbfb8aa3b, v198
	v_mul_f32_e32 v199, 0xbfb8aa3b, v199
	v_mul_f32_e32 v200, 0xbfb8aa3b, v200
	v_mul_f32_e32 v201, 0xbfb8aa3b, v201
	v_mul_f32_e32 v202, 0xbfb8aa3b, v202
	v_mul_f32_e32 v203, 0xbfb8aa3b, v203
	v_mul_f32_e32 v204, 0xbfb8aa3b, v204
	v_mul_f32_e32 v205, 0xbfb8aa3b, v205
	v_exp_f32_e32 v198, v198
	v_exp_f32_e32 v199, v199
	v_exp_f32_e32 v200, v200
	v_exp_f32_e32 v201, v201
	v_exp_f32_e32 v202, v202
	v_exp_f32_e32 v203, v203
	v_exp_f32_e32 v204, v204
	v_exp_f32_e32 v205, v205
	v_add_f32_e32 v198, 1.0, v198
	v_add_f32_e32 v199, 1.0, v199
	v_add_f32_e32 v200, 1.0, v200
	v_add_f32_e32 v201, 1.0, v201
	v_add_f32_e32 v202, 1.0, v202
	v_add_f32_e32 v203, 1.0, v203
	v_add_f32_e32 v204, 1.0, v204
	v_add_f32_e32 v205, 1.0, v205
	v_rcp_f32_e32 v198, v198
	v_rcp_f32_e32 v199, v199
	v_rcp_f32_e32 v200, v200
	v_rcp_f32_e32 v201, v201
	v_rcp_f32_e32 v202, v202
	v_rcp_f32_e32 v203, v203
	v_rcp_f32_e32 v204, v204
	v_rcp_f32_e32 v205, v205
	v_mul_f32_e32 v0, v0, v198
	v_mul_f32_e32 v1, v1, v199
	v_mul_f32_e32 v2, v2, v200
	v_mul_f32_e32 v3, v3, v201
	v_mul_f32_e32 v4, v4, v202
	v_mul_f32_e32 v5, v5, v203
	v_mul_f32_e32 v6, v6, v204
	v_mul_f32_e32 v7, v7, v205
	v_cvt_pk_bf16_f32 v0, v0, v101
	v_cvt_pk_bf16_f32 v1, v1, v101
	v_cvt_pk_bf16_f32 v2, v2, v101
	v_cvt_pk_bf16_f32 v3, v3, v101
	v_cvt_pk_bf16_f32 v4, v4, v101
	v_cvt_pk_bf16_f32 v5, v5, v101
	v_cvt_pk_bf16_f32 v6, v6, v101
	v_cvt_pk_bf16_f32 v7, v7, v101
	ds_write_b16 v195, v0 offset:32
	ds_write_b16 v195, v1 offset:176
	ds_write_b16 v195, v2 offset:320
	ds_write_b16 v195, v3 offset:464
	ds_write_b16 v195, v4 offset:2336
	ds_write_b16 v195, v5 offset:2480
	ds_write_b16 v195, v6 offset:2624
	ds_write_b16 v195, v7 offset:2768
	s_waitcnt lgkmcnt(0)
	global_load_dwordx4 v[92:95], v[146:147], off
	global_load_dwordx4 v[88:91], v[148:149], off
	global_load_dwordx4 v[84:87], v[150:151], off
	global_load_dwordx4 v[80:83], v[152:153], off
	ds_read_b128 v[250:253], v192 offset:64
	s_waitcnt vmcnt(11) lgkmcnt(0)
	v_mfma_f32_32x32x16_bf16 v[0:15], v[250:253], v[76:79], 0
	global_load_dwordx4 v[60:63], v[154:155], off
	global_load_dwordx4 v[56:59], v[154:155], off offset:1024
	global_load_dwordx4 v[48:51], v[154:155], off offset:2048
	global_load_dwordx4 v[52:55], v[154:155], off offset:3072
	s_waitcnt vmcnt(14)
	v_mfma_f32_32x32x16_bf16 v[214:229], v[250:253], v[72:75], 0
	s_waitcnt vmcnt(13)
	v_mfma_f32_32x32x16_bf16 v[234:249], v[250:253], v[68:71], 0
	s_waitcnt vmcnt(12)
; __device__ __forceinline__ float bf_lo(unsigned w) { return __uint_as_float(w << 16); }
; __device__ __forceinline__ float bf_hi(unsigned w) { return __uint_as_float(w & 0xffff0000u); }
; #define LAS __attribute__((address_space(3)))
; #define LDS_FENCE() asm volatile("s_waitcnt lgkmcnt(0)" ::: "memory")
; __device__ __forceinline__ unsigned cvt_pk_c(float lo, float hi) { const v2f v = {lo, hi}; const bf16x2_t b = __builtin_convertvector(v, bf16x2_t); return __builtin_bit_cast(unsigned, b); }
; template <bool PASS2>
; __device__ __forceinline__ void s5_tile(const Ctx& C, int T, int sb_lo, int sb_hi, LAS unsigned char* lds, int wave, int lane) {
;     ...
;             for (int cb = 0; cb < 4; ++cb) {
;                 v16f acc;
; #pragma unroll
;                 for (int r = 0; r < 16; ++r) acc[r] = 0.f;
;                 acc = __builtin_amdgcn_mfma_f32_32x32x16_bf16(bb[cb], a, acc, 0, 0, 0);
; #pragma unroll
;                 for (int rg = 0; rg < 4; ++rg) { v2u w; w.x = cvt_pk_c(acc[4 * rg], acc[4 * rg + 1]); w.y = cvt_pk_c(acc[4 * rg + 2], acc[4 * rg + 3]);
;                     *(LAS v2u*)(BH + tl * BH_STRIDE + cb * 32 + 8 * rg + 4 * hh) = w; }
;             }
;             LDS_FENCE();
;             {
;                 unsigned bu[32];
; #pragma unroll
;                 for (int t = 0; t < 32; ++t) bu[t] = *(const LAS unsigned*)(BH + t * BH_STRIDE + 2 * lane);
;                 LDS_FENCE();
;                 float xr = sr[gi], xi = si[gi];
; #pragma unroll
;                 for (int t = 0; t < 32; ++t) {
;                     if (sample && t == 0) { xr = s0ar; xi = s0ai; }
;                     if (sample && t == 16) { xr = s0br; xi = s0bi; }
;                     const float nr = fmaf(lr[gi], xr, fmaf(-li[gi], xi, bf_lo(bu[t]))), ni = fmaf(lr[gi], xi, fmaf(li[gi], xr, bf_hi(bu[t])));
;                     xr = nr; xi = ni;
;                     if (PASS2) {
;                         *(LAS unsigned*)(BH + t * BH_STRIDE + 2 * lane) = cvt_pk_nv(xr, xi);
;                         if (sample && (t & 15) == 15) { const int seq = 2 * sb + (t >> 4);
;                             C.out()[OFF_SRE_S + ((size_t)seq * NG + g) * NP + lane] = xr; C.out()[OFF_SIM_S + ((size_t)seq * NG + g) * NP + lane] = xi; }
;                     }
;                 }
;                 sr[gi] = xr; si[gi] = xi;
	v_mfma_f32_32x32x16_bf16 v[198:213], v[250:253], v[64:67], 0
	s_nop 11
	v_permlane32_swap_b32_e32 v0, v234
	v_permlane32_swap_b32_e32 v1, v235
	v_permlane32_swap_b32_e32 v2, v236
	v_permlane32_swap_b32_e32 v3, v237
	v_permlane32_swap_b32_e32 v4, v238
	v_permlane32_swap_b32_e32 v5, v239
	v_permlane32_swap_b32_e32 v6, v240
	v_permlane32_swap_b32_e32 v7, v241
	v_permlane32_swap_b32_e32 v8, v242
	v_permlane32_swap_b32_e32 v9, v243
	v_permlane32_swap_b32_e32 v10, v244
	v_permlane32_swap_b32_e32 v11, v245
	v_permlane32_swap_b32_e32 v12, v246
	v_permlane32_swap_b32_e32 v13, v247
	v_permlane32_swap_b32_e32 v14, v248
	v_permlane32_swap_b32_e32 v15, v249
	v_permlane32_swap_b32_e32 v214, v198
	v_permlane32_swap_b32_e32 v215, v199
	v_permlane32_swap_b32_e32 v216, v200
	v_permlane32_swap_b32_e32 v217, v201
	v_permlane32_swap_b32_e32 v218, v202
	v_permlane32_swap_b32_e32 v219, v203
	v_permlane32_swap_b32_e32 v220, v204
	v_permlane32_swap_b32_e32 v221, v205
	v_permlane32_swap_b32_e32 v222, v206
	v_permlane32_swap_b32_e32 v223, v207
	v_permlane32_swap_b32_e32 v224, v208
	v_permlane32_swap_b32_e32 v225, v209
	v_permlane32_swap_b32_e32 v226, v210
	v_permlane32_swap_b32_e32 v227, v211
	v_permlane32_swap_b32_e32 v228, v212
	v_permlane32_swap_b32_e32 v229, v213
	v_fma_f32 v0, -v180, v108, v0
	v_fma_f32 v214, v180, v110, v214
	v_fma_f32 v110, v179, v110, v0
	v_fma_f32 v108, v179, v108, v214
	v_cvt_pk_bf16_f32 v197, v110, v108
	ds_write_b32 v107, v197 offset:4608
	v_fma_f32 v1, -v180, v108, v1
	v_fma_f32 v215, v180, v110, v215
	v_fma_f32 v110, v179, v110, v1
	v_fma_f32 v108, v179, v108, v215
	v_cvt_pk_bf16_f32 v197, v110, v108
	ds_write_b32 v107, v197 offset:4880
	v_fma_f32 v2, -v180, v108, v2
	v_fma_f32 v216, v180, v110, v216
	v_fma_f32 v110, v179, v110, v2
	v_fma_f32 v108, v179, v108, v216
	v_cvt_pk_bf16_f32 v197, v110, v108
	ds_write_b32 v107, v197 offset:5152
	v_fma_f32 v3, -v180, v108, v3
	v_fma_f32 v217, v180, v110, v217
	v_fma_f32 v110, v179, v110, v3
	v_fma_f32 v108, v179, v108, v217
	v_cvt_pk_bf16_f32 v197, v110, v108
	ds_write_b32 v107, v197 offset:5424
	v_fma_f32 v234, -v180, v108, v234
	v_fma_f32 v198, v180, v110, v198
	v_fma_f32 v110, v179, v110, v234
	v_fma_f32 v108, v179, v108, v198
	v_cvt_pk_bf16_f32 v197, v110, v108
	ds_write_b32 v107, v197 offset:5696
	v_fma_f32 v235, -v180, v108, v235
	v_fma_f32 v199, v180, v110, v199
	v_fma_f32 v110, v179, v110, v235
	v_fma_f32 v108, v179, v108, v199
	v_cvt_pk_bf16_f32 v197, v110, v108
	ds_write_b32 v107, v197 offset:5968
	v_fma_f32 v236, -v180, v108, v236
	v_fma_f32 v200, v180, v110, v200
	v_fma_f32 v110, v179, v110, v236
	v_fma_f32 v108, v179, v108, v200
	v_cvt_pk_bf16_f32 v197, v110, v108
	ds_write_b32 v107, v197 offset:6240
	v_fma_f32 v237, -v180, v108, v237
	v_fma_f32 v201, v180, v110, v201
	v_fma_f32 v110, v179, v110, v237
	v_fma_f32 v108, v179, v108, v201
	v_cvt_pk_bf16_f32 v197, v110, v108
	ds_write_b32 v107, v197 offset:6512
	v_fma_f32 v4, -v180, v108, v4
	v_fma_f32 v218, v180, v110, v218
	v_fma_f32 v110, v179, v110, v4
	v_fma_f32 v108, v179, v108, v218
	v_cvt_pk_bf16_f32 v197, v110, v108
	ds_write_b32 v107, v197 offset:6784
	v_fma_f32 v5, -v180, v108, v5
	v_fma_f32 v219, v180, v110, v219
	v_fma_f32 v110, v179, v110, v5
	v_fma_f32 v108, v179, v108, v219
	v_cvt_pk_bf16_f32 v197, v110, v108
	ds_write_b32 v107, v197 offset:7056
	v_fma_f32 v6, -v180, v108, v6
	v_fma_f32 v220, v180, v110, v220
	v_fma_f32 v110, v179, v110, v6
	v_fma_f32 v108, v179, v108, v220
	v_cvt_pk_bf16_f32 v197, v110, v108
	ds_write_b32 v107, v197 offset:7328
	v_fma_f32 v7, -v180, v108, v7
	v_fma_f32 v221, v180, v110, v221
	v_fma_f32 v110, v179, v110, v7
	v_fma_f32 v108, v179, v108, v221
	v_cvt_pk_bf16_f32 v197, v110, v108
	ds_write_b32 v107, v197 offset:7600
	v_fma_f32 v238, -v180, v108, v238
	v_fma_f32 v202, v180, v110, v202
	v_fma_f32 v110, v179, v110, v238
	v_fma_f32 v108, v179, v108, v202
	v_cvt_pk_bf16_f32 v197, v110, v108
	ds_write_b32 v107, v197 offset:7872
	v_fma_f32 v239, -v180, v108, v239
	v_fma_f32 v203, v180, v110, v203
	v_fma_f32 v110, v179, v110, v239
	v_fma_f32 v108, v179, v108, v203
	v_cvt_pk_bf16_f32 v197, v110, v108
	ds_write_b32 v107, v197 offset:8144
	v_fma_f32 v240, -v180, v108, v240
	v_fma_f32 v204, v180, v110, v204
	v_fma_f32 v110, v179, v110, v240
	v_fma_f32 v108, v179, v108, v204
	v_cvt_pk_bf16_f32 v197, v110, v108
	ds_write_b32 v107, v197 offset:8416
	v_fma_f32 v241, -v180, v108, v241
	v_fma_f32 v205, v180, v110, v205
	v_fma_f32 v110, v179, v110, v241
	v_fma_f32 v108, v179, v108, v205
	v_cvt_pk_bf16_f32 v197, v110, v108
	ds_write_b32 v107, v197 offset:8688
	v_fma_f32 v8, -v180, v108, v8
	v_fma_f32 v222, v180, v110, v222
	v_fma_f32 v110, v179, v110, v8
	v_fma_f32 v108, v179, v108, v222
	v_cvt_pk_bf16_f32 v197, v110, v108
	ds_write_b32 v107, v197 offset:8960
	v_fma_f32 v9, -v180, v108, v9
	v_fma_f32 v223, v180, v110, v223
	v_fma_f32 v110, v179, v110, v9
	v_fma_f32 v108, v179, v108, v223
	v_cvt_pk_bf16_f32 v197, v110, v108
	ds_write_b32 v107, v197 offset:9232
	v_fma_f32 v10, -v180, v108, v10
	v_fma_f32 v224, v180, v110, v224
	v_fma_f32 v110, v179, v110, v10
	v_fma_f32 v108, v179, v108, v224
	v_cvt_pk_bf16_f32 v197, v110, v108
	ds_write_b32 v107, v197 offset:9504
	v_fma_f32 v11, -v180, v108, v11
	v_fma_f32 v225, v180, v110, v225
	v_fma_f32 v110, v179, v110, v11
	v_fma_f32 v108, v179, v108, v225
	v_cvt_pk_bf16_f32 v197, v110, v108
	ds_write_b32 v107, v197 offset:9776
	v_fma_f32 v242, -v180, v108, v242
	v_fma_f32 v206, v180, v110, v206
	v_fma_f32 v110, v179, v110, v242
	v_fma_f32 v108, v179, v108, v206
	v_cvt_pk_bf16_f32 v197, v110, v108
	ds_write_b32 v107, v197 offset:10048
	v_fma_f32 v243, -v180, v108, v243
; __device__ __forceinline__ float bf_lo(unsigned w) { return __uint_as_float(w << 16); }
; __device__ __forceinline__ float bf_hi(unsigned w) { return __uint_as_float(w & 0xffff0000u); }
; __device__ __forceinline__ float gelu_t(float x) { const float u = 1.5957691216057308f * (x + 0.044715f * x * x * x); return x * sigmoid_f(u); }
; #define LAS __attribute__((address_space(3)))
; #define LDS_FENCE() asm volatile("s_waitcnt lgkmcnt(0)" ::: "memory")
; template <bool PASS2>
; __device__ __forceinline__ void s5_tile(const Ctx& C, int T, int sb_lo, int sb_hi, LAS unsigned char* lds, int wave, int lane) {
;     ...
;                 for (int t = 0; t < 32; ++t) {
;                     if (sample && t == 0) { xr = s0ar; xi = s0ai; }
;                     if (sample && t == 16) { xr = s0br; xi = s0bi; }
;                     const float nr = fmaf(lr[gi], xr, fmaf(-li[gi], xi, bf_lo(bu[t]))), ni = fmaf(lr[gi], xi, fmaf(li[gi], xr, bf_hi(bu[t])));
;                     xr = nr; xi = ni;
;                     if (PASS2) {
;                         *(LAS unsigned*)(BH + t * BH_STRIDE + 2 * lane) = cvt_pk_nv(xr, xi);
;                         if (sample && (t & 15) == 15) { const int seq = 2 * sb + (t >> 4);
;                             C.out()[OFF_SRE_S + ((size_t)seq * NG + g) * NP + lane] = xr; C.out()[OFF_SIM_S + ((size_t)seq * NG + g) * NP + lane] = xi; }
;                     }
;                 }
;                 sr[gi] = xr; si[gi] = xi;
;             }
;             LDS_FENCE();
;             if (PASS2) {
; #pragma unroll
;                 for (int rb = 0; rb < 2; ++rb) {
;                     v4f acc = (v4f){0.f, 0.f, 0.f, 0.f};
; #pragma unroll
;                     for (int ks = 0; ks < 4; ++ks) {
;                         const bfx8 sa = *(const LAS bfx8*)(BH + (16 * rb + fr) * BH_STRIDE + 32 * ks + 8 * kq);
;                         acc = __builtin_amdgcn_mfma_f32_16x16x32_bf16(sa, cm[ks], acc, 0, 0, 0);
;                     }
; #pragma unroll
;                     for (int r = 0; r < 4; ++r) {
;                         LAS bf16* up = XU + (16 * rb + 4 * kq + r) * XU_STRIDE + 16 * gi + fr;
;                         const float u = __uint_as_float((unsigned)(*up) << 16);
;                         *up = f2bf(gelu_t(acc[r] + dsk[gi] * u));
;                     }
;                 }
;                 LDS_FENCE();
	v_fma_f32 v207, v180, v110, v207
	v_fma_f32 v110, v179, v110, v243
	v_fma_f32 v108, v179, v108, v207
	v_cvt_pk_bf16_f32 v197, v110, v108
	ds_write_b32 v107, v197 offset:10320
	v_fma_f32 v244, -v180, v108, v244
	v_fma_f32 v208, v180, v110, v208
	v_fma_f32 v110, v179, v110, v244
	v_fma_f32 v108, v179, v108, v208
	v_cvt_pk_bf16_f32 v197, v110, v108
	ds_write_b32 v107, v197 offset:10592
	v_fma_f32 v245, -v180, v108, v245
	v_fma_f32 v209, v180, v110, v209
	v_fma_f32 v110, v179, v110, v245
	v_fma_f32 v108, v179, v108, v209
	v_cvt_pk_bf16_f32 v197, v110, v108
	ds_write_b32 v107, v197 offset:10864
	v_fma_f32 v12, -v180, v108, v12
	v_fma_f32 v226, v180, v110, v226
	v_fma_f32 v110, v179, v110, v12
	v_fma_f32 v108, v179, v108, v226
	v_cvt_pk_bf16_f32 v197, v110, v108
	ds_write_b32 v107, v197 offset:11136
	v_fma_f32 v13, -v180, v108, v13
	v_fma_f32 v227, v180, v110, v227
	v_fma_f32 v110, v179, v110, v13
	v_fma_f32 v108, v179, v108, v227
	v_cvt_pk_bf16_f32 v197, v110, v108
	ds_write_b32 v107, v197 offset:11408
	v_fma_f32 v14, -v180, v108, v14
	v_fma_f32 v228, v180, v110, v228
	v_fma_f32 v110, v179, v110, v14
	v_fma_f32 v108, v179, v108, v228
	v_cvt_pk_bf16_f32 v197, v110, v108
	ds_write_b32 v107, v197 offset:11680
	v_fma_f32 v15, -v180, v108, v15
	v_fma_f32 v229, v180, v110, v229
	v_fma_f32 v110, v179, v110, v15
	v_fma_f32 v108, v179, v108, v229
	v_cvt_pk_bf16_f32 v197, v110, v108
	ds_write_b32 v107, v197 offset:11952
	v_fma_f32 v246, -v180, v108, v246
	v_fma_f32 v210, v180, v110, v210
	v_fma_f32 v110, v179, v110, v246
	v_fma_f32 v108, v179, v108, v210
	v_cvt_pk_bf16_f32 v197, v110, v108
	ds_write_b32 v107, v197 offset:12224
	v_fma_f32 v247, -v180, v108, v247
	v_fma_f32 v211, v180, v110, v211
	v_fma_f32 v110, v179, v110, v247
	v_fma_f32 v108, v179, v108, v211
	v_cvt_pk_bf16_f32 v197, v110, v108
	ds_write_b32 v107, v197 offset:12496
	v_fma_f32 v248, -v180, v108, v248
	v_fma_f32 v212, v180, v110, v212
	v_fma_f32 v110, v179, v110, v248
	v_fma_f32 v108, v179, v108, v212
	v_cvt_pk_bf16_f32 v197, v110, v108
	ds_write_b32 v107, v197 offset:12768
	v_fma_f32 v249, -v180, v108, v249
	v_fma_f32 v213, v180, v110, v213
	v_fma_f32 v110, v179, v110, v249
	v_fma_f32 v108, v179, v108, v213
	v_cvt_pk_bf16_f32 v197, v110, v108
	ds_write_b32 v107, v197 offset:13040
	s_waitcnt lgkmcnt(0)
	ds_read_b128 v[214:217], v194 offset:4608
	ds_read_b128 v[218:221], v194 offset:4672
	ds_read_b128 v[222:225], v194 offset:4736
	ds_read_b128 v[226:229], v194 offset:4800
	ds_read_b128 v[234:237], v194 offset:8960
	ds_read_b128 v[238:241], v194 offset:9024
	ds_read_b128 v[242:245], v194 offset:9088
	ds_read_b128 v[246:249], v194 offset:9152
	ds_read_u16 v8, v195 offset:64
	ds_read_u16 v9, v195 offset:208
	ds_read_u16 v10, v195 offset:352
	ds_read_u16 v11, v195 offset:496
	ds_read_u16 v12, v195 offset:2368
	ds_read_u16 v13, v195 offset:2512
	ds_read_u16 v14, v195 offset:2656
	ds_read_u16 v15, v195 offset:2800
	s_waitcnt vmcnt(8) lgkmcnt(8)
	v_mfma_f32_16x16x32_bf16 v[0:3], v[214:217], v[44:47], 0
	v_mfma_f32_16x16x32_bf16 v[4:7], v[234:237], v[44:47], 0
	v_mfma_f32_16x16x32_bf16 v[0:3], v[218:221], v[40:43], v[0:3]
	v_mfma_f32_16x16x32_bf16 v[4:7], v[238:241], v[40:43], v[4:7]
	v_mfma_f32_16x16x32_bf16 v[0:3], v[222:225], v[32:35], v[0:3]
	v_mfma_f32_16x16x32_bf16 v[4:7], v[242:245], v[32:35], v[4:7]
	v_mfma_f32_16x16x32_bf16 v[0:3], v[226:229], v[36:39], v[0:3]
	v_mfma_f32_16x16x32_bf16 v[4:7], v[246:249], v[36:39], v[4:7]
	s_waitcnt lgkmcnt(0)
	v_lshlrev_b32_e32 v8, 16, v8
	v_lshlrev_b32_e32 v9, 16, v9
	v_lshlrev_b32_e32 v10, 16, v10
	v_lshlrev_b32_e32 v11, 16, v11
	v_lshlrev_b32_e32 v12, 16, v12
	v_lshlrev_b32_e32 v13, 16, v13
	v_lshlrev_b32_e32 v14, 16, v14
	v_lshlrev_b32_e32 v15, 16, v15
	v_fma_f32 v0, v181, v8, v0
	v_fma_f32 v1, v181, v9, v1
	v_fma_f32 v2, v181, v10, v2
	v_fma_f32 v3, v181, v11, v3
	v_fma_f32 v4, v181, v12, v4
	v_fma_f32 v5, v181, v13, v5
	v_fma_f32 v6, v181, v14, v6
	v_fma_f32 v7, v181, v15, v7
	v_mul_f32_e32 v198, 0x3d372713, v0
	v_mul_f32_e32 v199, 0x3d372713, v1
	v_mul_f32_e32 v200, 0x3d372713, v2
	v_mul_f32_e32 v201, 0x3d372713, v3
	v_mul_f32_e32 v202, 0x3d372713, v4
	v_mul_f32_e32 v203, 0x3d372713, v5
	v_mul_f32_e32 v204, 0x3d372713, v6
	v_mul_f32_e32 v205, 0x3d372713, v7
	v_mul_f32_e32 v198, v0, v198
	v_mul_f32_e32 v199, v1, v199
	v_mul_f32_e32 v200, v2, v200
	v_mul_f32_e32 v201, v3, v201
	v_mul_f32_e32 v202, v4, v202
	v_mul_f32_e32 v203, v5, v203
	v_mul_f32_e32 v204, v6, v204
	v_mul_f32_e32 v205, v7, v205
	v_fma_f32 v198, v0, v198, v0
	v_fma_f32 v199, v1, v199, v1
	v_fma_f32 v200, v2, v200, v2
	v_fma_f32 v201, v3, v201, v3
	v_fma_f32 v202, v4, v202, v4
	v_fma_f32 v203, v5, v203, v5
	v_fma_f32 v204, v6, v204, v6
	v_fma_f32 v205, v7, v205, v7
	v_mul_f32_e32 v198, 0x3fcc422a, v198
	v_mul_f32_e32 v199, 0x3fcc422a, v199
	v_mul_f32_e32 v200, 0x3fcc422a, v200
	v_mul_f32_e32 v201, 0x3fcc422a, v201
	v_mul_f32_e32 v202, 0x3fcc422a, v202
	v_mul_f32_e32 v203, 0x3fcc422a, v203
	v_mul_f32_e32 v204, 0x3fcc422a, v204
	v_mul_f32_e32 v205, 0x3fcc422a, v205
	v_mul_f32_e32 v198, 0xbfb8aa3b, v198
	v_mul_f32_e32 v199, 0xbfb8aa3b, v199
	v_mul_f32_e32 v200, 0xbfb8aa3b, v200
	v_mul_f32_e32 v201, 0xbfb8aa3b, v201
	v_mul_f32_e32 v202, 0xbfb8aa3b, v202
	v_mul_f32_e32 v203, 0xbfb8aa3b, v203
	v_mul_f32_e32 v204, 0xbfb8aa3b, v204
	v_mul_f32_e32 v205, 0xbfb8aa3b, v205
	v_exp_f32_e32 v198, v198
	v_exp_f32_e32 v199, v199
	v_exp_f32_e32 v200, v200
	v_exp_f32_e32 v201, v201
	v_exp_f32_e32 v202, v202
	v_exp_f32_e32 v203, v203
	v_exp_f32_e32 v204, v204
	v_exp_f32_e32 v205, v205
	v_add_f32_e32 v198, 1.0, v198
	v_add_f32_e32 v199, 1.0, v199
	v_add_f32_e32 v200, 1.0, v200
	v_add_f32_e32 v201, 1.0, v201
	v_add_f32_e32 v202, 1.0, v202
	v_add_f32_e32 v203, 1.0, v203
	v_add_f32_e32 v204, 1.0, v204
	v_add_f32_e32 v205, 1.0, v205
	v_rcp_f32_e32 v198, v198
	v_rcp_f32_e32 v199, v199
	v_rcp_f32_e32 v200, v200
	v_rcp_f32_e32 v201, v201
	v_rcp_f32_e32 v202, v202
	v_rcp_f32_e32 v203, v203
	v_rcp_f32_e32 v204, v204
	v_rcp_f32_e32 v205, v205
	v_mul_f32_e32 v0, v0, v198
	v_mul_f32_e32 v1, v1, v199
	v_mul_f32_e32 v2, v2, v200
	v_mul_f32_e32 v3, v3, v201
	v_mul_f32_e32 v4, v4, v202
	v_mul_f32_e32 v5, v5, v203
	v_mul_f32_e32 v6, v6, v204
	v_mul_f32_e32 v7, v7, v205
	v_cvt_pk_bf16_f32 v0, v0, v101
	v_cvt_pk_bf16_f32 v1, v1, v101
	v_cvt_pk_bf16_f32 v2, v2, v101
	v_cvt_pk_bf16_f32 v3, v3, v101
	v_cvt_pk_bf16_f32 v4, v4, v101
	v_cvt_pk_bf16_f32 v5, v5, v101
	v_cvt_pk_bf16_f32 v6, v6, v101
	v_cvt_pk_bf16_f32 v7, v7, v101
	ds_write_b16 v195, v0 offset:64
	ds_write_b16 v195, v1 offset:208
	ds_write_b16 v195, v2 offset:352
	ds_write_b16 v195, v3 offset:496
	ds_write_b16 v195, v4 offset:2368
	ds_write_b16 v195, v5 offset:2512
	ds_write_b16 v195, v6 offset:2656
	ds_write_b16 v195, v7 offset:2800
	s_waitcnt lgkmcnt(0)
; #define LAS __attribute__((address_space(3)))
; template <bool PASS2>
; __device__ __forceinline__ void s5_tile(const Ctx& C, int T, int sb_lo, int sb_hi, LAS unsigned char* lds, int wave, int lane) {
;     ...
;         for (int gi = 0; gi < 4; ++gi) {
;             const int g = wave * 4 + gi, gnx = wave * 4 + ((gi + 1) & 3);
;             bfx8 bb[4], cm[4];
; #pragma unroll
;             for (int cb = 0; cb < 4; ++cb) { bb[cb] = bbn[cb]; bbn[cb] = *(const bfx8*)(BBt + ((size_t)(gnx * 128 + cb * 32 + tl)) * GN + 8 * hh); }
;             if (PASS2) {
; #pragma unroll
;                 for (int ks = 0; ks < 4; ++ks) { cm[ks] = cmn[ks]; cmn[ks] = *(const bfx8*)(CMt + ((size_t)(gnx * GN + fr)) * 128 + 32 * ks + 8 * kq); }
;             }
;             float s0ar = 0.f, s0ai = 0.f, s0br = 0.f, s0bi = 0.f;
;             if (sample) { const size_t o0 = ((size_t)(2 * sb) * NG + g) * NP + lane, o1 = o0 + (size_t)NG * NP;
;                 s0ar = C.in(2)[o0]; s0ai = C.in(3)[o0]; s0br = C.in(2)[o1]; s0bi = C.in(3)[o1]; }
;             const bfx8 a = *(const LAS bfx8*)(XU + tl * XU_STRIDE + 16 * gi + 8 * hh);
; #pragma unroll
;             for (int cb = 0; cb < 4; ++cb) {
;                 v16f acc;
; #pragma unroll
;                 for (int r = 0; r < 16; ++r) acc[r] = 0.f;
;                 acc = __builtin_amdgcn_mfma_f32_32x32x16_bf16(bb[cb], a, acc, 0, 0, 0);
; #pragma unroll
;                 for (int rg = 0; rg < 4; ++rg) { v2u w; w.x = cvt_pk_c(acc[4 * rg], acc[4 * rg + 1]); w.y = cvt_pk_c(acc[4 * rg + 2], acc[4 * rg + 3]);
;                     *(LAS v2u*)(BH + tl * BH_STRIDE + cb * 32 + 8 * rg + 4 * hh) = w; }
;             }
;             LDS_FENCE();
;             {
;                 unsigned bu[32];
; #pragma unroll
;                 for (int t = 0; t < 32; ++t) bu[t] = *(const LAS unsigned*)(BH + t * BH_STRIDE + 2 * lane);
;                 LDS_FENCE();
;                 float xr = sr[gi], xi = si[gi];
; #pragma unroll
;                 for (int t = 0; t < 32; ++t) {
;                     if (sample && t == 0) { xr = s0ar; xi = s0ai; }
;                     if (sample && t == 16) { xr = s0br; xi = s0bi; }
;                     const float nr = fmaf(lr[gi], xr, fmaf(-li[gi], xi, bf_lo(bu[t]))), ni = fmaf(lr[gi], xi, fmaf(li[gi], xr, bf_hi(bu[t])));
;                     xr = nr; xi = ni;
;                     if (PASS2) {
	global_load_dwordx4 v[76:79], v[124:125], off
	global_load_dwordx4 v[72:75], v[122:123], off
	global_load_dwordx4 v[68:71], v[120:121], off
	global_load_dwordx4 v[64:67], v[118:119], off
	ds_read_b128 v[250:253], v192 offset:96
	s_waitcnt vmcnt(11) lgkmcnt(0)
	v_mfma_f32_32x32x16_bf16 v[0:15], v[250:253], v[92:95], 0
	global_load_dwordx4 v[44:47], v[156:157], off
	global_load_dwordx4 v[40:43], v[156:157], off offset:1024
	global_load_dwordx4 v[36:39], v[156:157], off offset:2048
	global_load_dwordx4 v[32:35], v[156:157], off offset:3072
	s_waitcnt vmcnt(14)
	v_mfma_f32_32x32x16_bf16 v[214:229], v[250:253], v[88:91], 0
	s_waitcnt vmcnt(13)
	v_mfma_f32_32x32x16_bf16 v[234:249], v[250:253], v[84:87], 0
	s_waitcnt vmcnt(12)
	v_mfma_f32_32x32x16_bf16 v[198:213], v[250:253], v[80:83], 0
	s_nop 11
	v_permlane32_swap_b32_e32 v0, v234
	v_permlane32_swap_b32_e32 v1, v235
	v_permlane32_swap_b32_e32 v2, v236
	v_permlane32_swap_b32_e32 v3, v237
	v_permlane32_swap_b32_e32 v4, v238
	v_permlane32_swap_b32_e32 v5, v239
	v_permlane32_swap_b32_e32 v6, v240
	v_permlane32_swap_b32_e32 v7, v241
	v_permlane32_swap_b32_e32 v8, v242
	v_permlane32_swap_b32_e32 v9, v243
	v_permlane32_swap_b32_e32 v10, v244
	v_permlane32_swap_b32_e32 v11, v245
	v_permlane32_swap_b32_e32 v12, v246
	v_permlane32_swap_b32_e32 v13, v247
	v_permlane32_swap_b32_e32 v14, v248
	v_permlane32_swap_b32_e32 v15, v249
	v_permlane32_swap_b32_e32 v214, v198
	v_permlane32_swap_b32_e32 v215, v199
	v_permlane32_swap_b32_e32 v216, v200
	v_permlane32_swap_b32_e32 v217, v201
	v_permlane32_swap_b32_e32 v218, v202
	v_permlane32_swap_b32_e32 v219, v203
	v_permlane32_swap_b32_e32 v220, v204
	v_permlane32_swap_b32_e32 v221, v205
	v_permlane32_swap_b32_e32 v222, v206
	v_permlane32_swap_b32_e32 v223, v207
	v_permlane32_swap_b32_e32 v224, v208
	v_permlane32_swap_b32_e32 v225, v209
	v_permlane32_swap_b32_e32 v226, v210
	v_permlane32_swap_b32_e32 v227, v211
	v_permlane32_swap_b32_e32 v228, v212
	v_permlane32_swap_b32_e32 v229, v213
	v_fma_f32 v0, -v190, v109, v0
	v_fma_f32 v214, v190, v111, v214
	v_fma_f32 v111, v189, v111, v0
	v_fma_f32 v109, v189, v109, v214
	v_cvt_pk_bf16_f32 v197, v111, v109
	ds_write_b32 v107, v197 offset:4608
	v_fma_f32 v1, -v190, v109, v1
	v_fma_f32 v215, v190, v111, v215
	v_fma_f32 v111, v189, v111, v1
	v_fma_f32 v109, v189, v109, v215
	v_cvt_pk_bf16_f32 v197, v111, v109
	ds_write_b32 v107, v197 offset:4880
	v_fma_f32 v2, -v190, v109, v2
	v_fma_f32 v216, v190, v111, v216
	v_fma_f32 v111, v189, v111, v2
	v_fma_f32 v109, v189, v109, v216
	v_cvt_pk_bf16_f32 v197, v111, v109
	ds_write_b32 v107, v197 offset:5152
	v_fma_f32 v3, -v190, v109, v3
	v_fma_f32 v217, v190, v111, v217
	v_fma_f32 v111, v189, v111, v3
	v_fma_f32 v109, v189, v109, v217
	v_cvt_pk_bf16_f32 v197, v111, v109
	ds_write_b32 v107, v197 offset:5424
	v_fma_f32 v234, -v190, v109, v234
	v_fma_f32 v198, v190, v111, v198
	v_fma_f32 v111, v189, v111, v234
	v_fma_f32 v109, v189, v109, v198
	v_cvt_pk_bf16_f32 v197, v111, v109
	ds_write_b32 v107, v197 offset:5696
	v_fma_f32 v235, -v190, v109, v235
	v_fma_f32 v199, v190, v111, v199
	v_fma_f32 v111, v189, v111, v235
	v_fma_f32 v109, v189, v109, v199
	v_cvt_pk_bf16_f32 v197, v111, v109
	ds_write_b32 v107, v197 offset:5968
	v_fma_f32 v236, -v190, v109, v236
	v_fma_f32 v200, v190, v111, v200
	v_fma_f32 v111, v189, v111, v236
	v_fma_f32 v109, v189, v109, v200
	v_cvt_pk_bf16_f32 v197, v111, v109
	ds_write_b32 v107, v197 offset:6240
	v_fma_f32 v237, -v190, v109, v237
	v_fma_f32 v201, v190, v111, v201
	v_fma_f32 v111, v189, v111, v237
	v_fma_f32 v109, v189, v109, v201
	v_cvt_pk_bf16_f32 v197, v111, v109
	ds_write_b32 v107, v197 offset:6512
	v_fma_f32 v4, -v190, v109, v4
	v_fma_f32 v218, v190, v111, v218
	v_fma_f32 v111, v189, v111, v4
	v_fma_f32 v109, v189, v109, v218
	v_cvt_pk_bf16_f32 v197, v111, v109
	ds_write_b32 v107, v197 offset:6784
	v_fma_f32 v5, -v190, v109, v5
	v_fma_f32 v219, v190, v111, v219
	v_fma_f32 v111, v189, v111, v5
	v_fma_f32 v109, v189, v109, v219
	v_cvt_pk_bf16_f32 v197, v111, v109
	ds_write_b32 v107, v197 offset:7056
	v_fma_f32 v6, -v190, v109, v6
	v_fma_f32 v220, v190, v111, v220
	v_fma_f32 v111, v189, v111, v6
	v_fma_f32 v109, v189, v109, v220
	v_cvt_pk_bf16_f32 v197, v111, v109
	ds_write_b32 v107, v197 offset:7328
	v_fma_f32 v7, -v190, v109, v7
	v_fma_f32 v221, v190, v111, v221
	v_fma_f32 v111, v189, v111, v7
	v_fma_f32 v109, v189, v109, v221
	v_cvt_pk_bf16_f32 v197, v111, v109
	ds_write_b32 v107, v197 offset:7600
	v_fma_f32 v238, -v190, v109, v238
	v_fma_f32 v202, v190, v111, v202
	v_fma_f32 v111, v189, v111, v238
	v_fma_f32 v109, v189, v109, v202
	v_cvt_pk_bf16_f32 v197, v111, v109
	ds_write_b32 v107, v197 offset:7872
	v_fma_f32 v239, -v190, v109, v239
	v_fma_f32 v203, v190, v111, v203
	v_fma_f32 v111, v189, v111, v239
	v_fma_f32 v109, v189, v109, v203
	v_cvt_pk_bf16_f32 v197, v111, v109
	ds_write_b32 v107, v197 offset:8144
	v_fma_f32 v240, -v190, v109, v240
	v_fma_f32 v204, v190, v111, v204
	v_fma_f32 v111, v189, v111, v240
	v_fma_f32 v109, v189, v109, v204
	v_cvt_pk_bf16_f32 v197, v111, v109
	ds_write_b32 v107, v197 offset:8416
	v_fma_f32 v241, -v190, v109, v241
	v_fma_f32 v205, v190, v111, v205
	v_fma_f32 v111, v189, v111, v241
	v_fma_f32 v109, v189, v109, v205
	v_cvt_pk_bf16_f32 v197, v111, v109
	ds_write_b32 v107, v197 offset:8688
	v_fma_f32 v8, -v190, v109, v8
	v_fma_f32 v222, v190, v111, v222
	v_fma_f32 v111, v189, v111, v8
	v_fma_f32 v109, v189, v109, v222
	v_cvt_pk_bf16_f32 v197, v111, v109
	ds_write_b32 v107, v197 offset:8960
	v_fma_f32 v9, -v190, v109, v9
	v_fma_f32 v223, v190, v111, v223
	v_fma_f32 v111, v189, v111, v9
	v_fma_f32 v109, v189, v109, v223
; __device__ __forceinline__ float bf_lo(unsigned w) { return __uint_as_float(w << 16); }
; __device__ __forceinline__ float bf_hi(unsigned w) { return __uint_as_float(w & 0xffff0000u); }
; #define LAS __attribute__((address_space(3)))
; #define LDS_FENCE() asm volatile("s_waitcnt lgkmcnt(0)" ::: "memory")
; __device__ __forceinline__ unsigned cvt_pk_nv(float lo, float hi) { unsigned r; asm("v_cvt_pk_bf16_f32 %0, %1, %2" : "=v"(r) : "v"(lo), "v"(hi)); return r; }
;     __device__ __forceinline__ float* out() const { return (float*)karg_in(33); }
; template <bool PASS2>
; __device__ __forceinline__ void s5_tile(const Ctx& C, int T, int sb_lo, int sb_hi, LAS unsigned char* lds, int wave, int lane) {
;     ...
;                 for (int t = 0; t < 32; ++t) {
;                     if (sample && t == 0) { xr = s0ar; xi = s0ai; }
;                     if (sample && t == 16) { xr = s0br; xi = s0bi; }
;                     const float nr = fmaf(lr[gi], xr, fmaf(-li[gi], xi, bf_lo(bu[t]))), ni = fmaf(lr[gi], xi, fmaf(li[gi], xr, bf_hi(bu[t])));
;                     xr = nr; xi = ni;
;                     if (PASS2) {
;                         *(LAS unsigned*)(BH + t * BH_STRIDE + 2 * lane) = cvt_pk_nv(xr, xi);
;                         if (sample && (t & 15) == 15) { const int seq = 2 * sb + (t >> 4);
;                             C.out()[OFF_SRE_S + ((size_t)seq * NG + g) * NP + lane] = xr; C.out()[OFF_SIM_S + ((size_t)seq * NG + g) * NP + lane] = xi; }
;                     }
;                 }
;                 sr[gi] = xr; si[gi] = xi;
;             }
;             LDS_FENCE();
;             if (PASS2) {
; #pragma unroll
;                 for (int rb = 0; rb < 2; ++rb) {
;                     v4f acc = (v4f){0.f, 0.f, 0.f, 0.f};
; #pragma unroll
;                     for (int ks = 0; ks < 4; ++ks) {
;                         const bfx8 sa = *(const LAS bfx8*)(BH + (16 * rb + fr) * BH_STRIDE + 32 * ks + 8 * kq);
;                         acc = __builtin_amdgcn_mfma_f32_16x16x32_bf16(sa, cm[ks], acc, 0, 0, 0);
;                     }
	v_cvt_pk_bf16_f32 v197, v111, v109
	ds_write_b32 v107, v197 offset:9232
	v_fma_f32 v10, -v190, v109, v10
	v_fma_f32 v224, v190, v111, v224
	v_fma_f32 v111, v189, v111, v10
	v_fma_f32 v109, v189, v109, v224
	v_cvt_pk_bf16_f32 v197, v111, v109
	ds_write_b32 v107, v197 offset:9504
	v_fma_f32 v11, -v190, v109, v11
	v_fma_f32 v225, v190, v111, v225
	v_fma_f32 v111, v189, v111, v11
	v_fma_f32 v109, v189, v109, v225
	v_cvt_pk_bf16_f32 v197, v111, v109
	ds_write_b32 v107, v197 offset:9776
	v_fma_f32 v242, -v190, v109, v242
	v_fma_f32 v206, v190, v111, v206
	v_fma_f32 v111, v189, v111, v242
	v_fma_f32 v109, v189, v109, v206
	v_cvt_pk_bf16_f32 v197, v111, v109
	ds_write_b32 v107, v197 offset:10048
	v_fma_f32 v243, -v190, v109, v243
	v_fma_f32 v207, v190, v111, v207
	v_fma_f32 v111, v189, v111, v243
	v_fma_f32 v109, v189, v109, v207
	v_cvt_pk_bf16_f32 v197, v111, v109
	ds_write_b32 v107, v197 offset:10320
	v_fma_f32 v244, -v190, v109, v244
	v_fma_f32 v208, v190, v111, v208
	v_fma_f32 v111, v189, v111, v244
	v_fma_f32 v109, v189, v109, v208
	v_cvt_pk_bf16_f32 v197, v111, v109
	ds_write_b32 v107, v197 offset:10592
	v_fma_f32 v245, -v190, v109, v245
	v_fma_f32 v209, v190, v111, v209
	v_fma_f32 v111, v189, v111, v245
	v_fma_f32 v109, v189, v109, v209
	v_cvt_pk_bf16_f32 v197, v111, v109
	ds_write_b32 v107, v197 offset:10864
	v_fma_f32 v12, -v190, v109, v12
	v_fma_f32 v226, v190, v111, v226
	v_fma_f32 v111, v189, v111, v12
	v_fma_f32 v109, v189, v109, v226
	v_cvt_pk_bf16_f32 v197, v111, v109
	ds_write_b32 v107, v197 offset:11136
	v_fma_f32 v13, -v190, v109, v13
	v_fma_f32 v227, v190, v111, v227
	v_fma_f32 v111, v189, v111, v13
	v_fma_f32 v109, v189, v109, v227
	v_cvt_pk_bf16_f32 v197, v111, v109
	ds_write_b32 v107, v197 offset:11408
	v_fma_f32 v14, -v190, v109, v14
	v_fma_f32 v228, v190, v111, v228
	v_fma_f32 v111, v189, v111, v14
	v_fma_f32 v109, v189, v109, v228
	v_cvt_pk_bf16_f32 v197, v111, v109
	ds_write_b32 v107, v197 offset:11680
	v_fma_f32 v15, -v190, v109, v15
	v_fma_f32 v229, v190, v111, v229
	v_fma_f32 v111, v189, v111, v15
	v_fma_f32 v109, v189, v109, v229
	v_cvt_pk_bf16_f32 v197, v111, v109
	ds_write_b32 v107, v197 offset:11952
	v_fma_f32 v246, -v190, v109, v246
	v_fma_f32 v210, v190, v111, v210
	v_fma_f32 v111, v189, v111, v246
	v_fma_f32 v109, v189, v109, v210
	v_cvt_pk_bf16_f32 v197, v111, v109
	ds_write_b32 v107, v197 offset:12224
	v_fma_f32 v247, -v190, v109, v247
	v_fma_f32 v211, v190, v111, v211
	v_fma_f32 v111, v189, v111, v247
	v_fma_f32 v109, v189, v109, v211
	v_cvt_pk_bf16_f32 v197, v111, v109
	ds_write_b32 v107, v197 offset:12496
	v_fma_f32 v248, -v190, v109, v248
	v_fma_f32 v212, v190, v111, v212
	v_fma_f32 v111, v189, v111, v248
	v_fma_f32 v109, v189, v109, v212
	v_cvt_pk_bf16_f32 v197, v111, v109
	ds_write_b32 v107, v197 offset:12768
	v_fma_f32 v249, -v190, v109, v249
	v_fma_f32 v213, v190, v111, v213
	v_fma_f32 v111, v189, v111, v249
	v_fma_f32 v109, v189, v109, v213
	v_cvt_pk_bf16_f32 v197, v111, v109
	ds_write_b32 v107, v197 offset:13040
	s_waitcnt lgkmcnt(0)
	ds_read_b128 v[214:217], v194 offset:4608
	ds_read_b128 v[218:221], v194 offset:4672
	ds_read_b128 v[222:225], v194 offset:4736
	ds_read_b128 v[226:229], v194 offset:4800
	ds_read_b128 v[234:237], v194 offset:8960
	ds_read_b128 v[238:241], v194 offset:9024
	ds_read_b128 v[242:245], v194 offset:9088
	ds_read_b128 v[246:249], v194 offset:9152
	ds_read_u16 v8, v195 offset:96
	ds_read_u16 v9, v195 offset:240
	ds_read_u16 v10, v195 offset:384
	ds_read_u16 v11, v195 offset:528
	ds_read_u16 v12, v195 offset:2400
	ds_read_u16 v13, v195 offset:2544
	ds_read_u16 v14, v195 offset:2688
	ds_read_u16 v15, v195 offset:2832
	s_waitcnt vmcnt(8) lgkmcnt(8)
	v_mfma_f32_16x16x32_bf16 v[0:3], v[214:217], v[60:63], 0
	v_mfma_f32_16x16x32_bf16 v[4:7], v[234:237], v[60:63], 0
	v_mfma_f32_16x16x32_bf16 v[0:3], v[218:221], v[56:59], v[0:3]
	v_mfma_f32_16x16x32_bf16 v[4:7], v[238:241], v[56:59], v[4:7]
	v_mfma_f32_16x16x32_bf16 v[0:3], v[222:225], v[48:51], v[0:3]
	v_mfma_f32_16x16x32_bf16 v[4:7], v[242:245], v[48:51], v[4:7]
	v_mfma_f32_16x16x32_bf16 v[0:3], v[226:229], v[52:55], v[0:3]
	v_mfma_f32_16x16x32_bf16 v[4:7], v[246:249], v[52:55], v[4:7]
	s_waitcnt lgkmcnt(0)
; __device__ __forceinline__ float gelu_t(float x) { const float u = 1.5957691216057308f * (x + 0.044715f * x * x * x); return x * sigmoid_f(u); }
; #define LAS __attribute__((address_space(3)))
; #define LDS_FENCE() asm volatile("s_waitcnt lgkmcnt(0)" ::: "memory")
; __device__ __forceinline__ bf16 f2bf(float f) { return (bf16)(cvt_pk_nv(f, 0.f) & 0xffffu); }
; template <bool PASS2>
; __device__ __forceinline__ void s5_tile(const Ctx& C, int T, int sb_lo, int sb_hi, LAS unsigned char* lds, int wave, int lane) {
;     ...
; #pragma unroll
;                     for (int r = 0; r < 4; ++r) {
;                         LAS bf16* up = XU + (16 * rb + 4 * kq + r) * XU_STRIDE + 16 * gi + fr;
;                         const float u = __uint_as_float((unsigned)(*up) << 16);
;                         *up = f2bf(gelu_t(acc[r] + dsk[gi] * u));
;                     }
;                 }
;                 LDS_FENCE();
;             }
;         }
;         if (PASS2) {
; #pragma unroll
;             for (int i = 0; i < 4; ++i) *(v4u*)(C.YB() + (size_t)(rb0 + xrow + 8 * i) * BWD + 64 * wave + 8 * xpart) = *(const LAS v4u*)(XU + (xrow + 8 * i) * XU_STRIDE + 8 * xpart);
;             LDS_FENCE();
;         }
	v_lshlrev_b32_e32 v8, 16, v8
	v_lshlrev_b32_e32 v9, 16, v9
	v_lshlrev_b32_e32 v10, 16, v10
	v_lshlrev_b32_e32 v11, 16, v11
	v_lshlrev_b32_e32 v12, 16, v12
	v_lshlrev_b32_e32 v13, 16, v13
	v_lshlrev_b32_e32 v14, 16, v14
	v_lshlrev_b32_e32 v15, 16, v15
	v_fma_f32 v0, v191, v8, v0
	v_fma_f32 v1, v191, v9, v1
	v_fma_f32 v2, v191, v10, v2
	v_fma_f32 v3, v191, v11, v3
	v_fma_f32 v4, v191, v12, v4
	v_fma_f32 v5, v191, v13, v5
	v_fma_f32 v6, v191, v14, v6
	v_fma_f32 v7, v191, v15, v7
	v_mul_f32_e32 v198, 0x3d372713, v0
	v_mul_f32_e32 v199, 0x3d372713, v1
	v_mul_f32_e32 v200, 0x3d372713, v2
	v_mul_f32_e32 v201, 0x3d372713, v3
	v_mul_f32_e32 v202, 0x3d372713, v4
	v_mul_f32_e32 v203, 0x3d372713, v5
	v_mul_f32_e32 v204, 0x3d372713, v6
	v_mul_f32_e32 v205, 0x3d372713, v7
	v_mul_f32_e32 v198, v0, v198
	v_mul_f32_e32 v199, v1, v199
	v_mul_f32_e32 v200, v2, v200
	v_mul_f32_e32 v201, v3, v201
	v_mul_f32_e32 v202, v4, v202
	v_mul_f32_e32 v203, v5, v203
	v_mul_f32_e32 v204, v6, v204
	v_mul_f32_e32 v205, v7, v205
	v_fma_f32 v198, v0, v198, v0
	v_fma_f32 v199, v1, v199, v1
	v_fma_f32 v200, v2, v200, v2
	v_fma_f32 v201, v3, v201, v3
	v_fma_f32 v202, v4, v202, v4
	v_fma_f32 v203, v5, v203, v5
	v_fma_f32 v204, v6, v204, v6
	v_fma_f32 v205, v7, v205, v7
	v_mul_f32_e32 v198, 0x3fcc422a, v198
	v_mul_f32_e32 v199, 0x3fcc422a, v199
	v_mul_f32_e32 v200, 0x3fcc422a, v200
	v_mul_f32_e32 v201, 0x3fcc422a, v201
	v_mul_f32_e32 v202, 0x3fcc422a, v202
	v_mul_f32_e32 v203, 0x3fcc422a, v203
	v_mul_f32_e32 v204, 0x3fcc422a, v204
	v_mul_f32_e32 v205, 0x3fcc422a, v205
	v_mul_f32_e32 v198, 0xbfb8aa3b, v198
	v_mul_f32_e32 v199, 0xbfb8aa3b, v199
	v_mul_f32_e32 v200, 0xbfb8aa3b, v200
	v_mul_f32_e32 v201, 0xbfb8aa3b, v201
	v_mul_f32_e32 v202, 0xbfb8aa3b, v202
	v_mul_f32_e32 v203, 0xbfb8aa3b, v203
	v_mul_f32_e32 v204, 0xbfb8aa3b, v204
	v_mul_f32_e32 v205, 0xbfb8aa3b, v205
	v_exp_f32_e32 v198, v198
	v_exp_f32_e32 v199, v199
	v_exp_f32_e32 v200, v200
	v_exp_f32_e32 v201, v201
	v_exp_f32_e32 v202, v202
	v_exp_f32_e32 v203, v203
	v_exp_f32_e32 v204, v204
	v_exp_f32_e32 v205, v205
	v_add_f32_e32 v198, 1.0, v198
	v_add_f32_e32 v199, 1.0, v199
	v_add_f32_e32 v200, 1.0, v200
	v_add_f32_e32 v201, 1.0, v201
	v_add_f32_e32 v202, 1.0, v202
	v_add_f32_e32 v203, 1.0, v203
	v_add_f32_e32 v204, 1.0, v204
	v_add_f32_e32 v205, 1.0, v205
	v_rcp_f32_e32 v198, v198
	v_rcp_f32_e32 v199, v199
	v_rcp_f32_e32 v200, v200
	v_rcp_f32_e32 v201, v201
	v_rcp_f32_e32 v202, v202
	v_rcp_f32_e32 v203, v203
	v_rcp_f32_e32 v204, v204
	v_rcp_f32_e32 v205, v205
	v_mul_f32_e32 v0, v0, v198
	v_mul_f32_e32 v1, v1, v199
	v_mul_f32_e32 v2, v2, v200
	v_mul_f32_e32 v3, v3, v201
	v_mul_f32_e32 v4, v4, v202
	v_mul_f32_e32 v5, v5, v203
	v_mul_f32_e32 v6, v6, v204
	v_mul_f32_e32 v7, v7, v205
	v_cvt_pk_bf16_f32 v0, v0, v101
	v_cvt_pk_bf16_f32 v1, v1, v101
	v_cvt_pk_bf16_f32 v2, v2, v101
	v_cvt_pk_bf16_f32 v3, v3, v101
	v_cvt_pk_bf16_f32 v4, v4, v101
	v_cvt_pk_bf16_f32 v5, v5, v101
	v_cvt_pk_bf16_f32 v6, v6, v101
	v_cvt_pk_bf16_f32 v7, v7, v101
	ds_write_b16 v195, v0 offset:96
	ds_write_b16 v195, v1 offset:240
	ds_write_b16 v195, v2 offset:384
	ds_write_b16 v195, v3 offset:528
	ds_write_b16 v195, v4 offset:2400
	ds_write_b16 v195, v5 offset:2544
	ds_write_b16 v195, v6 offset:2688
	ds_write_b16 v195, v7 offset:2832
	v_ashrrev_i32_e32 v159, 31, v158
	v_lshlrev_b64 v[4:5], 10, v[158:159]
	s_waitcnt lgkmcnt(0)
	ds_read_b128 v[0:3], v196
	s_load_dwordx2 s[0:1], s[0:1], 0x110
	s_waitcnt lgkmcnt(0)
	v_lshl_add_u64 v[4:5], s[0:1], 0, v[4:5]
	v_lshl_add_u64 v[4:5], v[4:5], 0, s[10:11]
	v_lshl_add_u64 v[4:5], v[4:5], 0, v[100:101]
	v_add_co_u32_e32 v4, vcc, s47, v4
	s_mov_b64 s[0:1], s[80:81]
	s_nop 0
	v_addc_co_u32_e32 v5, vcc, 0, v5, vcc
	global_store_dwordx4 v[4:5], v[0:3], off
	ds_read_b128 v[0:3], v196 offset:1152
	s_load_dwordx2 s[0:1], s[0:1], 0x110
	v_add_u32_e32 v4, 8, v158
	v_ashrrev_i32_e32 v5, 31, v4
	v_lshlrev_b64 v[4:5], 10, v[4:5]
	s_waitcnt lgkmcnt(0)
	v_lshl_add_u64 v[4:5], s[0:1], 0, v[4:5]
	v_lshl_add_u64 v[4:5], v[4:5], 0, s[10:11]
	v_lshl_add_u64 v[4:5], v[4:5], 0, v[100:101]
	v_add_co_u32_e32 v4, vcc, s47, v4
	s_mov_b64 s[0:1], s[80:81]
	s_nop 0
	v_addc_co_u32_e32 v5, vcc, 0, v5, vcc
	global_store_dwordx4 v[4:5], v[0:3], off
	ds_read_b128 v[0:3], v196 offset:2304
	s_load_dwordx2 s[0:1], s[0:1], 0x110
	v_add_u32_e32 v4, 16, v158
	v_ashrrev_i32_e32 v5, 31, v4
	v_lshlrev_b64 v[4:5], 10, v[4:5]
	s_waitcnt lgkmcnt(0)
	v_lshl_add_u64 v[4:5], s[0:1], 0, v[4:5]
	v_lshl_add_u64 v[4:5], v[4:5], 0, s[10:11]
	v_lshl_add_u64 v[4:5], v[4:5], 0, v[100:101]
	v_add_co_u32_e32 v4, vcc, s47, v4
	s_mov_b64 s[0:1], s[80:81]
	s_nop 0
	v_addc_co_u32_e32 v5, vcc, 0, v5, vcc
	global_store_dwordx4 v[4:5], v[0:3], off
	ds_read_b128 v[0:3], v196 offset:3456
	s_load_dwordx2 s[0:1], s[0:1], 0x110
	v_add_u32_e32 v4, 24, v158
	v_ashrrev_i32_e32 v5, 31, v4
	v_lshlrev_b64 v[4:5], 10, v[4:5]
	s_waitcnt lgkmcnt(0)
	v_lshl_add_u64 v[4:5], s[0:1], 0, v[4:5]
	v_lshl_add_u64 v[4:5], v[4:5], 0, s[10:11]
	v_lshl_add_u64 v[4:5], v[4:5], 0, v[100:101]
	v_add_co_u32_e32 v4, vcc, 0x11300000, v4
	s_nop 1
	v_addc_co_u32_e32 v5, vcc, 0, v5, vcc
	global_store_dwordx4 v[4:5], v[0:3], off
	s_waitcnt lgkmcnt(0)
	s_cbranch_scc1 .LBB0_671

; #define FTID const int ftid_ = fresh_tid()
; #define WAVE (__builtin_amdgcn_readfirstlane(ftid_ >> 6))
; __global__ void __launch_bounds__(NTHREADS, 2) fwd_kernel(Args args) {
;     ...
;     { FTID; const bool swap0 = GSZ > 128;
;       for (int T = BX; T < NTILE - 1; T += GSZ) { if (swap0 && T == 0) continue; s5_tile<true>(C, T, 0, 4, lds, WAVE, LANE); }
;       if (swap0 && BX == 128) s5_tile<true>(C, 0, 0, 4, lds, WAVE, LANE);
;       if (BX >= 1 && BX <= 4) s5_tile<true>(C, NTILE - 1, BX - 1, BX, lds, WAVE, LANE);
;       if (BX == 0) { __syncthreads(); gmlp_tile(C, NTILE - 1, lds, WAVE, LANE, TID); } }
.LBB0_673:
	s_sub_i32 s0, s33, 0x81
	s_cmp_lt_u32 s0, 4
	s_cselect_b64 s[0:1], -1, 0
	s_and_b64 s[0:1], s[0:1], s[52:53]
	s_and_b64 vcc, exec, s[0:1]
	s_cbranch_vccz .Lmy_p6_no_t0
	s_cmp_lg_u32 s98, 0
	s_cbranch_scc1 .Lmy_p6_no_t0
	s_mov_b32 s98, 1
	s_sub_i32 s99, s33, 0x81
	s_lshl_b32 s99, s99, 5
	s_mov_b32 s77, 0
	s_mov_b32 s76, 0
	v_mov_b32_e32 v172, v162
	s_branch .Lmy_p6_tile_entry

; __global__ void __launch_bounds__(NTHREADS, 2) fwd_kernel(Args args) {
	.amdhsa_kernel _Z10fwd_kernel4Args
		.amdhsa_group_segment_fixed_size 0
		.amdhsa_private_segment_fixed_size 0
		.amdhsa_kernarg_size 536
		.amdhsa_user_sgpr_count 2
		.amdhsa_user_sgpr_dispatch_ptr 0
		.amdhsa_user_sgpr_queue_ptr 0
		.amdhsa_user_sgpr_kernarg_segment_ptr 1
		.amdhsa_user_sgpr_dispatch_id 0
		.amdhsa_user_sgpr_kernarg_preload_length 0
		.amdhsa_user_sgpr_kernarg_preload_offset 0
		.amdhsa_user_sgpr_private_segment_size 0
		.amdhsa_uses_dynamic_stack 0
		.amdhsa_enable_private_segment 0
		.amdhsa_system_sgpr_workgroup_id_x 1
		.amdhsa_system_sgpr_workgroup_id_y 0
		.amdhsa_system_sgpr_workgroup_id_z 0
		.amdhsa_system_sgpr_workgroup_info 0
		.amdhsa_system_vgpr_workitem_id 2
		.amdhsa_next_free_vgpr 256
		.amdhsa_next_free_sgpr 100
		.amdhsa_accum_offset 256
		.amdhsa_reserve_vcc 1
		.amdhsa_float_round_mode_32 0
		.amdhsa_float_round_mode_16_64 0
		.amdhsa_float_denorm_mode_32 3
		.amdhsa_float_denorm_mode_16_64 3
		.amdhsa_dx10_clamp 1
		.amdhsa_ieee_mode 1
		.amdhsa_fp16_overflow 0
		.amdhsa_tg_split 0
		.amdhsa_exception_fp_ieee_invalid_op 0
		.amdhsa_exception_fp_denorm_src 0
		.amdhsa_exception_fp_ieee_div_zero 0
		.amdhsa_exception_fp_ieee_overflow 0
		.amdhsa_exception_fp_ieee_underflow 0
		.amdhsa_exception_fp_ieee_inexact 0
		.amdhsa_exception_int_div_zero 0
	.end_amdhsa_kernel

; __global__ void __launch_bounds__(NTHREADS, 2) fwd_kernel(Args args) {
amdhsa.kernels:
  - .agpr_count:     0
    .args:
      - .offset:         0
        .size:           280
        .value_kind:     by_value
      - .offset:         280
        .size:           4
        .value_kind:     hidden_block_count_x
      - .offset:         284
        .size:           4
        .value_kind:     hidden_block_count_y
      - .offset:         288
        .size:           4
        .value_kind:     hidden_block_count_z
      - .offset:         292
        .size:           2
        .value_kind:     hidden_group_size_x
      - .offset:         294
        .size:           2
        .value_kind:     hidden_group_size_y
      - .offset:         296
        .size:           2
        .value_kind:     hidden_group_size_z
      - .offset:         298
        .size:           2
        .value_kind:     hidden_remainder_x
      - .offset:         300
        .size:           2
        .value_kind:     hidden_remainder_y
      - .offset:         302
        .size:           2
        .value_kind:     hidden_remainder_z
      - .offset:         320
        .size:           8
        .value_kind:     hidden_global_offset_x
      - .offset:         328
        .size:           8
        .value_kind:     hidden_global_offset_y
      - .offset:         336
        .size:           8
        .value_kind:     hidden_global_offset_z
      - .offset:         344
        .size:           2
        .value_kind:     hidden_grid_dims
      - .offset:         368
        .size:           8
        .value_kind:     hidden_multigrid_sync_arg
      - .offset:         400
        .size:           4
        .value_kind:     hidden_dynamic_lds_size
    .group_segment_fixed_size: 0
    .kernarg_segment_align: 8
    .kernarg_segment_size: 536
    .language:       OpenCL C
    .language_version:
      - 2
      - 0
    .max_flat_workgroup_size: 512
    .name:           _Z10fwd_kernel4Args
    .private_segment_fixed_size: 0
    .sgpr_count:     106
    .sgpr_spill_count: 11
    .symbol:         _Z10fwd_kernel4Args.kd
    .uniform_work_group_size: 1
    .uses_dynamic_stack: false
    .vgpr_count:     256
    .vgpr_spill_count: 0
    .wavefront_size: 64
